# attention row-max chains: self-max canonicalisations folded into the consuming max (fewer VALU ops per tile), one extra nop state keeps the MFMA read distance
# baseline (speedup 1.0000x reference)
; template <int DV, bool MASK>
; __device__ __forceinline__ void attn_softmax(f32x16 (&p)[2], f32x16 (&o)[DV / 32], float& m, float& l, float cs, int hi, int dq) {
; __device__ __forceinline__ void swa_unit(const bf16* Z, const float* sink  , bf16* Y, int b, int g, int blk, int cblk, LAS unsigned char* L, int tid) {
;     const int wave = tid >> 6, lane = tid & 63, r32 = lane & 31, hi = lane >> 5;
;     const bool latent = blk >= 0;
;     const int head = 8 * g + wave;
;     const int qrow0 = b * TB + (latent ? CTX + 64 * blk : 64 * cblk);
;     bf16x8 qf[2][4];
; #pragma unroll
;     for (int sb = 0; sb < 2; ++sb) { const bf16* qp = Z + (size_t)(qrow0 + 32 * sb + r32) * DINP + ZSQ + head * 64 + 8 * hi;
; #pragma unroll
;         for (int ks = 0; ks < 4; ++ks) qf[sb][ks] = *(const bf16x8*)(qp + 16 * ks); }
;     f32x16 o[2][2];
; #pragma unroll
;     for (int sb = 0; sb < 2; ++sb)
; #pragma unroll
;         for (int d = 0; d < 2; ++d)
; #pragma unroll
;             for (int e = 0; e < 16; ++e) o[sb][d][e] = 0.f;
;     const float sk = sink[head] * LOG2E;
;     float m[2] = {sk, sk}, l[2] = {hi == 0 ? 1.f : 0.f, hi == 0 ? 1.f : 0.f};
;     const float cs = 0.125f * LOG2E;
;     int wlo = 0, nwin = 0;
;     if (latent) { wlo = blk - 2 < 0 ? 0 : blk - 2; const int whi = blk + 2 > 127 ? 127 : blk + 2; nwin = whi - wlo + 1; }
;     const int ntiles = 4 + nwin;
;     const unsigned kgo = (unsigned)(((tid >> 3) * DINP + ZSK + (tid & 7) * 8) * 2), klo = (unsigned)((tid >> 3) * SWA_KSB + (tid & 7) * 16), vlo = (unsigned)((tid >> 3) * SWA_VRB + (tid & 7) * 16);
;     const int vtb = (4 * hi + ((lane & 15) >> 2)) * SWA_VRB + (16 * ((lane >> 4) & 1) + 4 * (lane & 3)) * 2;
;     const char* zb0 = (const char*)(Z + ((size_t)b * TB) * DINP + g * 64);
;     v4u kreg, vreg;
;     ...
;     SWA_LOAD(0); SWA_STORE(0);
;     __syncthreads();
;     for (int t = 0; t < ntiles; ++t) {
;         const bool more = t + 1 < ntiles;
;         if (more) SWA_LOAD(t + 1);
;         LAS const unsigned char* Kt = L + (t & 1) * SWA_BUF;
;         const int kpos0 = 64 * (wlo + t - 4);
;         const bool edge = t >= 4 && (wlo + t - 4 == blk - 2 || wlo + t - 4 == blk + 2);
; #pragma unroll
;         for (int sb = 0; sb < 2; ++sb) attn_tile<64, 64, SWA_KSB, SWA_VRB, true>(Kt, Kt + SWA_KT, qf[sb], o[sb], m[sb], l[sb], cs, r32, hi, vtb, edge ? kpos0 - (64 * blk + 32 * sb + r32) : NO_MASK);
.LBB0_832:
	s_mov_b64 s[2:3], -1
	s_cmpk_gt_i32 s8, 0x3ff
	v_add_u32_e32 v165, v174, v159
	v_lshlrev_b32_e32 v32, 1, v30
	s_cbranch_scc0 .LBB0_850
	s_add_i32 s2, s8, 0xfffffc00
	s_lshr_b32 s4, s2, 3
	s_bfe_u32 s5, s8, 0x10002
	s_lshl_b32 s3, s8, 6
	v_lshl_add_u32 v2, s5, 3, v1
	s_mul_i32 s2, s4, 0x2100
	s_and_b32 s3, s3, 0xc0
	s_or_b32 s2, s2, s3
	v_lshlrev_b32_e32 v4, 6, v2
	v_or_b32_e32 v146, s2, v31
	v_ashrrev_i32_e32 v5, 31, v4
	v_mov_b64_e32 v[6:7], s[66:67]
	v_mad_u64_u32 v[8:9], s[2:3], v146, s35, v[6:7]
	v_lshlrev_b64 v[142:143], 1, v[4:5]
	v_lshl_add_u64 v[4:5], v[8:9], 0, v[142:143]
	v_lshl_add_u64 v[4:5], v[4:5], 0, v[32:33]
	v_or_b32_e32 v144, 32, v146
	global_load_dwordx4 v[130:133], v[4:5], off offset:1664
	global_load_dwordx4 v[126:129], v[4:5], off offset:1696
	global_load_dwordx4 v[122:125], v[4:5], off offset:1728
	global_load_dwordx4 v[118:121], v[4:5], off offset:1760
	v_mad_u64_u32 v[4:5], s[2:3], v144, s35, v[6:7]
	s_mul_hi_u32 s2, s4, 0x3de0000
	s_mul_i32 s4, s4, 0x3de0000
	s_add_u32 s3, s66, s4
	s_addc_u32 s4, s67, s2
	s_lshl_b32 s2, s5, 7
	s_add_u32 s2, s3, s2
	v_lshl_add_u64 v[4:5], v[4:5], 0, v[142:143]
	v_ashrrev_i32_e32 v3, 31, v2
	s_addc_u32 s3, s4, 0
	v_lshl_add_u64 v[4:5], v[4:5], 0, v[32:33]
	v_lshl_add_u64 v[2:3], v[2:3], 2, s[18:19]
	s_waitcnt vmcnt(13)
	v_lshl_add_u64 v[148:149], s[2:3], 0, v[156:157]
	global_load_dwordx4 v[114:117], v[4:5], off offset:1664
	global_load_dwordx4 v[26:29], v[4:5], off offset:1696
	global_load_dwordx4 v[22:25], v[4:5], off offset:1728
	global_load_dwordx4 v[18:21], v[4:5], off offset:1760
	global_load_dword v106, v[2:3], off
	s_nop 0
	global_load_dwordx4 v[2:5], v[148:149], off
	global_load_dwordx4 v[6:9], v[148:149], off offset:256
	s_mov_b32 s2, 0x78000
	s_waitcnt vmcnt(1)
	ds_write_b128 v174, v[2:5]
	s_waitcnt vmcnt(0)
	ds_write_b128 v165, v[6:9] offset:9216
	v_add_co_u32_e32 v2, vcc, s2, v148
	s_waitcnt lgkmcnt(0)
	s_nop 0
	v_addc_co_u32_e32 v3, vcc, 0, v149, vcc
	s_barrier
	global_load_dwordx4 v[98:101], v[2:3], off
	global_load_dwordx4 v[102:105], v[2:3], off offset:256
	v_mul_f32_e32 v107, 0x3fb8aa3b, v106
	v_add_u32_e32 v145, v178, v160
	ds_read_b128 v[2:5], v145
	ds_read_b128 v[6:9], v145 offset:32
	ds_read_b128 v[10:13], v145 offset:4608
	ds_read_b128 v[14:17], v145 offset:4640
	s_waitcnt lgkmcnt(3)
	v_mfma_f32_32x32x16_bf16 v[50:65], v[2:5], v[130:133], 0
	ds_read_b128 v[2:5], v145 offset:64
	ds_read_b128 v[66:69], v145 offset:4672
	s_waitcnt lgkmcnt(3)
	v_mfma_f32_32x32x16_bf16 v[34:49], v[10:13], v[130:133], 0
	v_mfma_f32_32x32x16_bf16 v[50:65], v[6:9], v[126:129], v[50:65]
	ds_read_b128 v[6:9], v145 offset:96
	ds_read_b128 v[10:13], v145 offset:4704
	s_waitcnt lgkmcnt(4)
	v_mfma_f32_32x32x16_bf16 v[34:49], v[14:17], v[126:129], v[34:49]
	s_waitcnt lgkmcnt(3)
	v_mfma_f32_32x32x16_bf16 v[50:65], v[2:5], v[122:125], v[50:65]
	s_waitcnt lgkmcnt(2)
	v_mfma_f32_32x32x16_bf16 v[34:49], v[66:69], v[122:125], v[34:49]
	s_waitcnt lgkmcnt(1)
	v_mfma_f32_32x32x16_bf16 v[50:65], v[6:9], v[118:121], v[50:65]
	s_waitcnt lgkmcnt(0)
	v_mfma_f32_32x32x16_bf16 v[34:49], v[10:13], v[118:121], v[34:49]
	s_nop 10
	v_max_f32_e32 v2, v50, v51
	v_max_f32_e32 v5, v42, v43
	v_max_f32_e32 v3, v58, v59
	v_max3_f32 v4, v34, v35, v36
	v_max3_f32 v5, v5, v44, v45
	v_max3_f32 v2, v2, v52, v53
	v_max3_f32 v3, v3, v60, v61
	v_max3_f32 v4, v4, v37, v38
	v_max3_f32 v5, v5, v46, v47
	v_max3_f32 v2, v2, v54, v55
	v_max3_f32 v3, v3, v62, v63
	v_max3_f32 v4, v4, v39, v40
	v_max3_f32 v5, v5, v48, v49
	v_max3_f32 v2, v2, v56, v57
	v_max3_f32 v3, v3, v64, v65
	v_max3_f32 v4, v4, v41, v5
	v_max3_f32 v2, v2, v3, v4
	v_mov_b32_e32 v3, v2
	s_nop 1
	v_permlane32_swap_b32_e32 v2, v3
	v_max_f32_e32 v2, v2, v3
	v_mul_f32_e32 v2, 0x3e38aa3b, v2
	v_max_f32_e32 v66, v107, v2
	v_fma_f32 v2, v106, s52, -v66
	v_exp_f32_e32 v67, v2
	v_fmamk_f32 v2, v106, 0xbfb8aa3b, v66
	v_cmp_lt_f32_e32 vcc, s34, v2
	s_cmp_eq_u64 vcc, 0
	s_cselect_b64 vcc, -1, 0
	v_cndmask_b32_e32 v152, v66, v107, vcc
	v_fma_f32 v51, v51, s45, -v152
	v_exp_f32_e32 v66, v51
	v_fma_f32 v51, v52, s45, -v152
	v_fma_f32 v52, v53, s45, -v152
	v_fma_f32 v53, v55, s45, -v152
	v_fma_f32 v55, v57, s45, -v152
	v_fma_f32 v57, v59, s45, -v152
	v_fma_f32 v59, v61, s45, -v152
	v_fma_f32 v61, v63, s45, -v152
	v_fma_f32 v34, v34, s45, -v152
	v_mul_f32_e32 v2, 0, v67
	v_cndmask_b32_e64 v82, v67, 1.0, vcc
	v_exp_f32_e32 v67, v52
	v_fma_f32 v52, v54, s45, -v152
	v_exp_f32_e32 v54, v53
	v_fma_f32 v53, v56, s45, -v152
	v_fma_f32 v56, v58, s45, -v152
	v_exp_f32_e32 v58, v57
	v_fma_f32 v57, v60, s45, -v152
	v_fma_f32 v60, v62, s45, -v152
	v_exp_f32_e32 v62, v61
	v_fma_f32 v61, v64, s45, -v152
	v_exp_f32_e32 v64, v34
	v_fma_f32 v34, v35, s45, -v152
	v_exp_f32_e32 v68, v34
	v_fma_f32 v34, v36, s45, -v152
	v_fma_f32 v63, v65, s45, -v152
	v_exp_f32_e32 v65, v34
	v_fma_f32 v34, v37, s45, -v152
	v_exp_f32_e32 v69, v34
	v_fma_f32 v34, v38, s45, -v152
	v_exp_f32_e32 v70, v34
	v_fma_f32 v34, v39, s45, -v152
	v_exp_f32_e32 v72, v34
	v_fma_f32 v34, v40, s45, -v152
	v_exp_f32_e32 v71, v34
	v_fma_f32 v34, v41, s45, -v152
	v_exp_f32_e32 v73, v34
	v_fma_f32 v34, v42, s45, -v152
	v_exp_f32_e32 v74, v34
	v_fma_f32 v34, v43, s45, -v152
	v_exp_f32_e32 v76, v34
	v_fma_f32 v34, v44, s45, -v152
	v_fma_f32 v50, v50, s45, -v152
	v_exp_f32_e32 v75, v34
	v_fma_f32 v34, v45, s45, -v152
	v_exp_f32_e32 v50, v50
	v_exp_f32_e32 v51, v51
	v_exp_f32_e32 v77, v34
	v_fma_f32 v34, v46, s45, -v152
	v_exp_f32_e32 v52, v52
	v_exp_f32_e32 v53, v53
	v_exp_f32_e32 v55, v55
	v_exp_f32_e32 v78, v34
	v_fma_f32 v34, v47, s45, -v152
	v_exp_f32_e32 v56, v56
	v_exp_f32_e32 v57, v57
	v_exp_f32_e32 v59, v59
; #define LAS __attribute__((address_space(3)))
; __device__ __forceinline__ unsigned pk2(float lo, float hi) { return pg8::pkbf(lo, hi); }
; __device__ __forceinline__ float fexp2(float x) { return __builtin_amdgcn_exp2f(x); }
; #define SCHED_FENCE() __builtin_amdgcn_sched_barrier(0)
; #define PV_LOAD(dst, i) do { _Pragma("unroll") for (int d = 0; d < ND; ++d) { LAS const unsigned char* vp = vb + (16 * (i)) * VRB + d * 64; dst[2 * d] = tr_read(vp); dst[2 * d + 1] = tr_read(vp + 8 * VRB); } } while (0)
; #define PV_MMA(src, i) do { _Pragma("unroll") for (int d = 0; d < ND; ++d) { const bf16x8 vf = __builtin_shufflevector(src[2 * d], src[2 * d + 1], 0, 1, 2, 3, 4, 5, 6, 7); o[d] = MFMA32(vf, pf[i], o[d]); } } while (0)
; template <int DV, bool MASK>
; __device__ __forceinline__ void attn_softmax(f32x16 (&p)[2], f32x16 (&o)[DV / 32], float& m, float& l, float cs, int hi, int dq) {
;     ...
;     float ls0 = 0.f, ls1 = 0.f, ls2 = 0.f, ls3 = 0.f;
; #pragma unroll
;     for (int kvb = 0; kvb < 2; ++kvb)
; #pragma unroll
;         for (int e = 0; e < 16; e += 4) {
;             const float e0 = fexp2(fmaf(p[kvb][e], cs, -m)), e1 = fexp2(fmaf(p[kvb][e + 1], cs, -m)), e2 = fexp2(fmaf(p[kvb][e + 2], cs, -m)), e3 = fexp2(fmaf(p[kvb][e + 3], cs, -m));
;             p[kvb][e] = e0; p[kvb][e + 1] = e1; p[kvb][e + 2] = e2; p[kvb][e + 3] = e3; ls0 += e0; ls1 += e1; ls2 += e2; ls3 += e3; }
;     l += (ls0 + ls1) + (ls2 + ls3);
; }
; template <int DV, int VRB>
; __device__ __forceinline__ void attn_pv(LAS const unsigned char* Vt, const f32x16 (&p)[2], f32x16 (&o)[DV / 32], int vtb) {
;     constexpr int ND = DV / 32;
;     LAS const unsigned char* vb = Vt + vtb;
;     bf16x8 pf[4];
; #pragma unroll
;     for (int i = 0; i < 4; ++i) { const int kvb = i >> 1, s = i & 1;
;         v4u pw; pw.x = pk2(p[kvb][8 * s + 0], p[kvb][8 * s + 1]); pw.y = pk2(p[kvb][8 * s + 2], p[kvb][8 * s + 3]); pw.z = pk2(p[kvb][8 * s + 4], p[kvb][8 * s + 5]); pw.w = pk2(p[kvb][8 * s + 6], p[kvb][8 * s + 7]);
;         pf[i] = __builtin_bit_cast(bf16x8, pw); }
;     s16x4 va[2 * ND], vbq[2 * ND];
;     ...
;     PV_LOAD(va, 0); SCHED_FENCE();
;     PV_LOAD(vbq, 1); PV_MMA(va, 0); SCHED_FENCE();
;     PV_LOAD(va, 2); PV_MMA(vbq, 1); SCHED_FENCE();
;     PV_LOAD(vbq, 3); PV_MMA(va, 2); SCHED_FENCE();
;     PV_MMA(vbq, 3); SCHED_FENCE();
	v_exp_f32_e32 v80, v34
	v_fma_f32 v34, v48, s45, -v152
	v_exp_f32_e32 v60, v60
	v_exp_f32_e32 v61, v61
	v_exp_f32_e32 v63, v63
	v_exp_f32_e32 v79, v34
	v_fma_f32 v34, v49, s45, -v152
	v_exp_f32_e32 v81, v34
	v_pk_add_f32 v[34:35], v[50:51], 0 op_sel_hi:[1,0]
	v_pk_add_f32 v[36:37], v[66:67], 0 op_sel_hi:[1,0]
	v_pk_add_f32 v[34:35], v[52:53], v[34:35]
	v_pk_add_f32 v[36:37], v[54:55], v[36:37]
	v_pk_add_f32 v[34:35], v[56:57], v[34:35]
	v_pk_add_f32 v[36:37], v[58:59], v[36:37]
	v_pk_add_f32 v[34:35], v[60:61], v[34:35]
	v_pk_add_f32 v[36:37], v[62:63], v[36:37]
	v_pk_add_f32 v[34:35], v[64:65], v[34:35]
	v_pk_add_f32 v[36:37], v[68:69], v[36:37]
	v_pk_add_f32 v[34:35], v[70:71], v[34:35]
	v_pk_add_f32 v[36:37], v[72:73], v[36:37]
	v_pk_add_f32 v[34:35], v[74:75], v[34:35]
	v_pk_add_f32 v[36:37], v[76:77], v[36:37]
	v_pk_add_f32 v[34:35], v[78:79], v[34:35]
	v_pk_add_f32 v[36:37], v[80:81], v[36:37]
	v_cvt_pk_bf16_f32 v42, v64, v68
	v_pk_add_f32 v[34:35], v[34:35], v[36:37]
	v_cvt_pk_bf16_f32 v43, v65, v69
	v_add_f32_e32 v153, v34, v35
	v_cvt_pk_bf16_f32 v34, v50, v66
	v_cvt_pk_bf16_f32 v35, v51, v67
	ds_read_b64_tr_b16 v[46:47], v179 offset:9216
	ds_read_b64_tr_b16 v[48:49], v179 offset:10752
	ds_read_b64_tr_b16 v[68:69], v179 offset:10816
	ds_read_b64_tr_b16 v[66:67], v179 offset:9280
	v_cndmask_b32_e64 v2, v2, 0, vcc
	v_mov_b32_e32 v3, v2
	v_mov_b32_e32 v4, v2
	v_mov_b32_e32 v5, v2
	v_mov_b32_e32 v6, v2
	v_mov_b32_e32 v7, v2
	v_mov_b32_e32 v8, v2
	v_mov_b32_e32 v9, v2
	v_mov_b32_e32 v10, v2
	v_mov_b32_e32 v11, v2
	v_mov_b32_e32 v12, v2
	v_mov_b32_e32 v13, v2
	v_mov_b32_e32 v14, v2
	v_mov_b32_e32 v15, v2
	v_mov_b32_e32 v16, v2
	v_mov_b32_e32 v17, v2
	v_fmac_f32_e32 v153, v170, v82
	v_cvt_pk_bf16_f32 v36, v52, v54
	v_cvt_pk_bf16_f32 v37, v53, v55
	v_cvt_pk_bf16_f32 v38, v56, v58
	v_cvt_pk_bf16_f32 v39, v57, v59
	v_cvt_pk_bf16_f32 v40, v60, v62
	v_cvt_pk_bf16_f32 v41, v61, v63
	v_cvt_pk_bf16_f32 v44, v70, v72
	v_cvt_pk_bf16_f32 v45, v71, v73
	v_cvt_pk_bf16_f32 v70, v74, v76
	v_cvt_pk_bf16_f32 v71, v75, v77
	v_cvt_pk_bf16_f32 v72, v78, v80
	v_cvt_pk_bf16_f32 v73, v79, v81
	s_waitcnt lgkmcnt(2)
	v_mfma_f32_32x32x16_bf16 v[50:65], v[46:49], v[34:37], v[2:17]
	ds_read_b64_tr_b16 v[46:47], v179 offset:12288
	ds_read_b64_tr_b16 v[48:49], v179 offset:13824
	ds_read_b64_tr_b16 v[76:77], v179 offset:13888
	ds_read_b64_tr_b16 v[74:75], v179 offset:12352
	s_waitcnt lgkmcnt(4)
	v_mfma_f32_32x32x16_bf16 v[2:17], v[66:69], v[34:37], v[2:17]
	s_waitcnt lgkmcnt(2)
	v_mfma_f32_32x32x16_bf16 v[50:65], v[46:49], v[38:41], v[50:65]
	ds_read_b64_tr_b16 v[34:35], v179 offset:15360
	ds_read_b64_tr_b16 v[36:37], v179 offset:16896
	ds_read_b64_tr_b16 v[48:49], v179 offset:16960
	ds_read_b64_tr_b16 v[46:47], v179 offset:15424
	s_waitcnt lgkmcnt(4)
	v_mfma_f32_32x32x16_bf16 v[2:17], v[74:77], v[38:41], v[2:17]
	s_waitcnt lgkmcnt(2)
	v_mfma_f32_32x32x16_bf16 v[50:65], v[34:37], v[42:45], v[50:65]
	ds_read_b64_tr_b16 v[34:35], v179 offset:18432
	ds_read_b64_tr_b16 v[36:37], v179 offset:19968
	ds_read_b64_tr_b16 v[40:41], v179 offset:20032
	ds_read_b64_tr_b16 v[38:39], v179 offset:18496
	s_waitcnt lgkmcnt(4)
	v_mfma_f32_32x32x16_bf16 v[2:17], v[46:49], v[42:45], v[2:17]
	s_waitcnt lgkmcnt(2)
	v_mfma_f32_32x32x16_bf16 v[50:65], v[34:37], v[70:73], v[50:65]
	s_waitcnt lgkmcnt(0)
	v_mfma_f32_32x32x16_bf16 v[2:17], v[38:41], v[70:73], v[2:17]
	ds_read_b128 v[34:37], v145
	ds_read_b128 v[38:41], v145 offset:32
	ds_read_b128 v[42:45], v145 offset:4608
	ds_read_b128 v[46:49], v145 offset:4640
	s_waitcnt lgkmcnt(3)
	v_mfma_f32_32x32x16_bf16 v[82:97], v[34:37], v[114:117], 0
	ds_read_b128 v[34:37], v145 offset:64
	ds_read_b128 v[108:111], v145 offset:4672
	s_waitcnt lgkmcnt(3)
	v_mfma_f32_32x32x16_bf16 v[66:81], v[42:45], v[114:117], 0
	v_mfma_f32_32x32x16_bf16 v[82:97], v[38:41], v[26:29], v[82:97]
	ds_read_b128 v[38:41], v145 offset:96
	ds_read_b128 v[42:45], v145 offset:4704
	s_waitcnt lgkmcnt(4)
	v_mfma_f32_32x32x16_bf16 v[66:81], v[46:49], v[26:29], v[66:81]
	s_waitcnt lgkmcnt(3)
	v_mfma_f32_32x32x16_bf16 v[82:97], v[34:37], v[22:25], v[82:97]
	s_waitcnt lgkmcnt(2)
	v_mfma_f32_32x32x16_bf16 v[66:81], v[108:111], v[22:25], v[66:81]
	s_waitcnt lgkmcnt(1)
	v_mfma_f32_32x32x16_bf16 v[82:97], v[38:41], v[18:21], v[82:97]
	s_waitcnt lgkmcnt(0)
; template <int DV, bool MASK>
; __device__ __forceinline__ void attn_softmax(f32x16 (&p)[2], f32x16 (&o)[DV / 32], float& m, float& l, float cs, int hi, int dq) {
;     if (MASK) { if (__builtin_amdgcn_readfirstlane(dq) != NO_MASK) {
; #pragma unroll
;         for (int kvb = 0; kvb < 2; ++kvb)
; #pragma unroll
;             for (int e = 0; e < 16; ++e) { const int rel = dq + 32 * kvb + (e & 3) + 8 * (e >> 2) + 4 * hi; if (rel > 128 || rel < -128) p[kvb][e] = -INFINITY; } } }
;     float mx;
;     {
;         float a0 = fmaxf(fmaxf(p[0][0], p[0][1]), p[0][2]), a1 = fmaxf(fmaxf(p[0][8], p[0][9]), p[0][10]), a2 = fmaxf(fmaxf(p[1][0], p[1][1]), p[1][2]), a3 = fmaxf(fmaxf(p[1][8], p[1][9]), p[1][10]);
;         a0 = fmaxf(fmaxf(a0, p[0][3]), p[0][4]); a1 = fmaxf(fmaxf(a1, p[0][11]), p[0][12]); a2 = fmaxf(fmaxf(a2, p[1][3]), p[1][4]); a3 = fmaxf(fmaxf(a3, p[1][11]), p[1][12]);
;         a0 = fmaxf(fmaxf(a0, p[0][5]), p[0][6]); a1 = fmaxf(fmaxf(a1, p[0][13]), p[0][14]); a2 = fmaxf(fmaxf(a2, p[1][5]), p[1][6]); a3 = fmaxf(fmaxf(a3, p[1][13]), p[1][14]);
;         a0 = fmaxf(a0, p[0][7]); a1 = fmaxf(a1, p[0][15]); a2 = fmaxf(a2, p[1][7]); a3 = fmaxf(a3, p[1][15]);
;         mx = fmaxf(fmaxf(a0, a1), fmaxf(a2, a3));
;         const auto rr = __builtin_amdgcn_permlane32_swap(__float_as_uint(mx), __float_as_uint(mx), false, false);
;         mx = fmaxf(__uint_as_float(rr[0]), __uint_as_float(rr[1])); }
;     const float mn = fmaxf(m, mx * cs);
;     if (__any(mn - m > ATT_THR)) {
;         const float alpha = fexp2(m - mn); m = mn; l *= alpha;
; #pragma unroll
;         for (int d = 0; d < DV / 32; ++d)
; #pragma unroll
;             for (int e = 0; e < 16; ++e) o[d][e] *= alpha;
;     }
;     float ls0 = 0.f, ls1 = 0.f, ls2 = 0.f, ls3 = 0.f;
; #pragma unroll
;     for (int kvb = 0; kvb < 2; ++kvb)
; #pragma unroll
;         for (int e = 0; e < 16; e += 4) {
;             const float e0 = fexp2(fmaf(p[kvb][e], cs, -m)), e1 = fexp2(fmaf(p[kvb][e + 1], cs, -m)), e2 = fexp2(fmaf(p[kvb][e + 2], cs, -m)), e3 = fexp2(fmaf(p[kvb][e + 3], cs, -m));
;             p[kvb][e] = e0; p[kvb][e + 1] = e1; p[kvb][e + 2] = e2; p[kvb][e + 3] = e3; ls0 += e0; ls1 += e1; ls2 += e2; ls3 += e3; }
;     l += (ls0 + ls1) + (ls2 + ls3);
; }
; template <int DV, int VRB>
; __device__ __forceinline__ void attn_pv(LAS const unsigned char* Vt, const f32x16 (&p)[2], f32x16 (&o)[DV / 32], int vtb) {
	v_mfma_f32_32x32x16_bf16 v[66:81], v[42:45], v[18:21], v[66:81]
	s_nop 10
	v_max_f32_e32 v34, v82, v83
	v_max_f32_e32 v37, v74, v75
	v_max_f32_e32 v35, v90, v91
	v_max3_f32 v36, v66, v67, v68
	v_max3_f32 v37, v37, v76, v77
	v_max3_f32 v34, v34, v84, v85
	v_max3_f32 v35, v35, v92, v93
	v_max3_f32 v36, v36, v69, v70
	v_max3_f32 v37, v37, v78, v79
	v_max3_f32 v34, v34, v86, v87
	v_max3_f32 v35, v35, v94, v95
	v_max3_f32 v36, v36, v71, v72
	v_max3_f32 v37, v37, v80, v81
	v_max3_f32 v34, v34, v88, v89
	v_max3_f32 v35, v35, v96, v97
	v_max3_f32 v36, v36, v73, v37
	v_max3_f32 v34, v34, v35, v36
	v_mov_b32_e32 v35, v34
	s_nop 1
	v_permlane32_swap_b32_e32 v34, v35
	v_max_f32_e32 v34, v34, v35
	v_mul_f32_e32 v34, 0x3e38aa3b, v34
	v_max_f32_e32 v108, v107, v34
	v_fma_f32 v34, v106, s52, -v108
	v_exp_f32_e32 v150, v34
	v_fmamk_f32 v34, v106, 0xbfb8aa3b, v108
	v_cmp_lt_f32_e32 vcc, s34, v34
	s_cmp_eq_u64 vcc, 0
	s_cselect_b64 s[2:3], -1, 0
	v_cndmask_b32_e64 v151, v108, v107, s[2:3]
	v_fma_f32 v82, v82, s45, -v151
	v_exp_f32_e32 v154, v82
	v_fma_f32 v82, v83, s45, -v151
	v_fma_f32 v66, v66, s45, -v151
	v_exp_f32_e32 v155, v82
	v_fma_f32 v82, v84, s45, -v151
	v_exp_f32_e32 v200, v66
	v_fma_f32 v66, v67, s45, -v151
	v_exp_f32_e32 v162, v82
	v_fma_f32 v82, v85, s45, -v151
	v_exp_f32_e32 v201, v66
	v_fma_f32 v66, v68, s45, -v151
	v_exp_f32_e32 v163, v82
	v_fma_f32 v82, v86, s45, -v151
	v_exp_f32_e32 v202, v66
	v_fma_f32 v66, v69, s45, -v151
	v_exp_f32_e32 v164, v82
	v_fma_f32 v82, v87, s45, -v151
	v_exp_f32_e32 v203, v66
	v_fma_f32 v66, v70, s45, -v151
	v_exp_f32_e32 v166, v82
	v_fma_f32 v82, v88, s45, -v151
	v_exp_f32_e32 v204, v66
	v_fma_f32 v66, v71, s45, -v151
	v_exp_f32_e32 v167, v82
	v_fma_f32 v82, v89, s45, -v151
	v_exp_f32_e32 v205, v66
	v_fma_f32 v66, v72, s45, -v151
	v_exp_f32_e32 v168, v82
	v_fma_f32 v82, v90, s45, -v151
	v_exp_f32_e32 v206, v66
	v_fma_f32 v66, v73, s45, -v151
	v_exp_f32_e32 v169, v82
	v_fma_f32 v82, v91, s45, -v151
	v_exp_f32_e32 v207, v66
	v_fma_f32 v66, v74, s45, -v151
	v_exp_f32_e32 v181, v82
	v_fma_f32 v82, v92, s45, -v151
	v_exp_f32_e32 v208, v66
	v_fma_f32 v66, v75, s45, -v151
	v_exp_f32_e32 v182, v82
	v_fma_f32 v82, v93, s45, -v151
	v_exp_f32_e32 v209, v66
	v_fma_f32 v66, v76, s45, -v151
	v_exp_f32_e32 v183, v82
	v_fma_f32 v82, v94, s45, -v151
	v_exp_f32_e32 v210, v66
	v_fma_f32 v66, v77, s45, -v151
	v_exp_f32_e32 v196, v82
	v_fma_f32 v82, v95, s45, -v151
	v_exp_f32_e32 v211, v66
	v_fma_f32 v66, v78, s45, -v151
	v_exp_f32_e32 v197, v82
	v_fma_f32 v82, v96, s45, -v151
	v_exp_f32_e32 v212, v66
	v_fma_f32 v66, v79, s45, -v151
	v_exp_f32_e32 v198, v82
	v_fma_f32 v82, v97, s45, -v151
	v_exp_f32_e32 v213, v66
	v_fma_f32 v66, v80, s45, -v151
	ds_read_b64_tr_b16 v[94:95], v179 offset:9216
	ds_read_b64_tr_b16 v[96:97], v179 offset:10752
	ds_read_b64_tr_b16 v[108:109], v179 offset:10816
	ds_read_b64_tr_b16 v[106:107], v179 offset:9280
	v_exp_f32_e32 v214, v66
	v_fma_f32 v66, v81, s45, -v151
	v_exp_f32_e32 v199, v82
	v_exp_f32_e32 v215, v66
	v_mul_f32_e32 v34, 0, v150
	v_cndmask_b32_e64 v34, v34, 0, s[2:3]
	v_mov_b32_e32 v35, v34
	v_mov_b32_e32 v36, v34
	v_mov_b32_e32 v37, v34
	v_mov_b32_e32 v38, v34
	v_mov_b32_e32 v39, v34
	v_mov_b32_e32 v40, v34
	v_mov_b32_e32 v41, v34
	v_mov_b32_e32 v42, v34
	v_mov_b32_e32 v43, v34
	v_mov_b32_e32 v44, v34
	v_mov_b32_e32 v45, v34
	v_mov_b32_e32 v46, v34
	v_mov_b32_e32 v47, v34
	v_mov_b32_e32 v48, v34
	v_mov_b32_e32 v49, v34
	v_cvt_pk_bf16_f32 v82, v154, v155
	v_cvt_pk_bf16_f32 v83, v162, v163
	v_cvt_pk_bf16_f32 v84, v164, v166
	v_cvt_pk_bf16_f32 v85, v167, v168
	v_cvt_pk_bf16_f32 v86, v169, v181
	v_cvt_pk_bf16_f32 v87, v182, v183
	v_cvt_pk_bf16_f32 v88, v196, v197
	v_cvt_pk_bf16_f32 v89, v198, v199
	v_cvt_pk_bf16_f32 v90, v200, v201
	v_cvt_pk_bf16_f32 v91, v202, v203
	v_cvt_pk_bf16_f32 v92, v204, v205
	v_cvt_pk_bf16_f32 v93, v206, v207
	v_cvt_pk_bf16_f32 v110, v208, v209
	v_cvt_pk_bf16_f32 v111, v210, v211
	v_cvt_pk_bf16_f32 v112, v212, v213
	v_cvt_pk_bf16_f32 v113, v214, v215
	s_waitcnt lgkmcnt(2)
	v_mfma_f32_32x32x16_bf16 v[66:81], v[94:97], v[82:85], v[34:49]
	ds_read_b64_tr_b16 v[94:95], v179 offset:12288
	ds_read_b64_tr_b16 v[96:97], v179 offset:13824
	ds_read_b64_tr_b16 v[136:137], v179 offset:13888
	ds_read_b64_tr_b16 v[134:135], v179 offset:12352
	s_waitcnt lgkmcnt(4)
	v_mfma_f32_32x32x16_bf16 v[34:49], v[106:109], v[82:85], v[34:49]
	s_waitcnt lgkmcnt(2)
	v_mfma_f32_32x32x16_bf16 v[66:81], v[94:97], v[86:89], v[66:81]
	ds_read_b64_tr_b16 v[82:83], v179 offset:15360
	ds_read_b64_tr_b16 v[84:85], v179 offset:16896
	ds_read_b64_tr_b16 v[96:97], v179 offset:16960
	ds_read_b64_tr_b16 v[94:95], v179 offset:15424
	s_waitcnt lgkmcnt(4)
	v_mfma_f32_32x32x16_bf16 v[34:49], v[134:137], v[86:89], v[34:49]
	s_waitcnt lgkmcnt(2)
	v_mfma_f32_32x32x16_bf16 v[66:81], v[82:85], v[90:93], v[66:81]
	ds_read_b64_tr_b16 v[82:83], v179 offset:18432
	ds_read_b64_tr_b16 v[84:85], v179 offset:19968
	ds_read_b64_tr_b16 v[88:89], v179 offset:20032
	ds_read_b64_tr_b16 v[86:87], v179 offset:18496
	s_waitcnt lgkmcnt(4)
	v_mfma_f32_32x32x16_bf16 v[34:49], v[94:97], v[90:93], v[34:49]
	s_waitcnt lgkmcnt(2)
	v_mfma_f32_32x32x16_bf16 v[66:81], v[82:85], v[110:113], v[66:81]
	s_waitcnt lgkmcnt(0)
	v_mfma_f32_32x32x16_bf16 v[34:49], v[86:89], v[110:113], v[34:49]
	s_mov_b32 s4, 0xf0000
	v_add_co_u32_e32 v82, vcc, s4, v148
	s_waitcnt vmcnt(1)
	ds_write_b128 v174, v[98:101] offset:21504
	s_waitcnt vmcnt(0)
	ds_write_b128 v165, v[102:105] offset:30720
	v_addc_co_u32_e32 v83, vcc, 0, v149, vcc
	s_waitcnt lgkmcnt(0)
	s_barrier
; #define LAS __attribute__((address_space(3)))
; #define SCHED_FENCE() __builtin_amdgcn_sched_barrier(0)
; template <int DQK, int KSB>
; __device__ __forceinline__ void attn_scores(LAS const unsigned char* Kt, const bf16x8 (&qf)[DQK / 16], f32x16 (&p)[2], int r32, int hi) {
;     constexpr int NK = DQK / 16;
;     LAS const unsigned char* kp = Kt + r32 * KSB + hi * 16;
;     f32x16 p0, p1;
; #pragma unroll
;     for (int e = 0; e < 16; ++e) { p0[e] = 0.f; p1[e] = 0.f; }
;     bf16x8 kr[3][2];
;     ...
;     QK_LOAD(0); QK_LOAD(1); SCHED_FENCE();
; #pragma unroll
;     for (int ks = 0; ks < NK; ++ks) {
;         if (ks + 2 < NK) QK_LOAD(ks + 2);
;         p0 = MFMA32(kr[ks % 3][0], qf[ks], p0); p1 = MFMA32(kr[ks % 3][1], qf[ks], p1); SCHED_FENCE();
;     }
;     ...
;     p[0] = p0; p[1] = p1;
; }
; template <int DV, bool MASK>
; __device__ __forceinline__ void attn_softmax(f32x16 (&p)[2], f32x16 (&o)[DV / 32], float& m, float& l, float cs, int hi, int dq) {
;     if (MASK) { if (__builtin_amdgcn_readfirstlane(dq) != NO_MASK) {
; #pragma unroll
;         for (int kvb = 0; kvb < 2; ++kvb)
; #pragma unroll
;             for (int e = 0; e < 16; ++e) { const int rel = dq + 32 * kvb + (e & 3) + 8 * (e >> 2) + 4 * hi; if (rel > 128 || rel < -128) p[kvb][e] = -INFINITY; } } }
;     float mx;
;     {
;         float a0 = fmaxf(fmaxf(p[0][0], p[0][1]), p[0][2]), a1 = fmaxf(fmaxf(p[0][8], p[0][9]), p[0][10]), a2 = fmaxf(fmaxf(p[1][0], p[1][1]), p[1][2]), a3 = fmaxf(fmaxf(p[1][8], p[1][9]), p[1][10]);
;         a0 = fmaxf(fmaxf(a0, p[0][3]), p[0][4]); a1 = fmaxf(fmaxf(a1, p[0][11]), p[0][12]); a2 = fmaxf(fmaxf(a2, p[1][3]), p[1][4]); a3 = fmaxf(fmaxf(a3, p[1][11]), p[1][12]);
; __device__ __forceinline__ void swa_unit(const bf16* Z, const float* sink  , bf16* Y, int b, int g, int blk, int cblk, LAS unsigned char* L, int tid) {
;     ...
;     for (int t = 0; t < ntiles; ++t) {
;         const bool more = t + 1 < ntiles;
;         if (more) SWA_LOAD(t + 1);
;         LAS const unsigned char* Kt = L + (t & 1) * SWA_BUF;
;         const int kpos0 = 64 * (wlo + t - 4);
;         const bool edge = t >= 4 && (wlo + t - 4 == blk - 2 || wlo + t - 4 == blk + 2);
; #pragma unroll
;         for (int sb = 0; sb < 2; ++sb) attn_tile<64, 64, SWA_KSB, SWA_VRB, true>(Kt, Kt + SWA_KT, qf[sb], o[sb], m[sb], l[sb], cs, r32, hi, vtb, edge ? kpos0 - (64 * blk + 32 * sb + r32) : NO_MASK);
	global_load_dwordx4 v[134:137], v[82:83], off
	global_load_dwordx4 v[138:141], v[82:83], off offset:256
	ds_read_b128 v[82:85], v145 offset:21504
	ds_read_b128 v[186:189], v145 offset:21536
	ds_read_b128 v[86:89], v145 offset:26112
	ds_read_b128 v[216:219], v145 offset:26144
	s_waitcnt lgkmcnt(3)
	v_mfma_f32_32x32x16_bf16 v[98:113], v[82:85], v[130:133], 0
	ds_read_b128 v[220:223], v145 offset:21568
	ds_read_b128 v[224:227], v145 offset:26176
	s_waitcnt lgkmcnt(3)
	v_mfma_f32_32x32x16_bf16 v[82:97], v[86:89], v[130:133], 0
	v_mfma_f32_32x32x16_bf16 v[98:113], v[186:189], v[126:129], v[98:113]
	ds_read_b128 v[186:189], v145 offset:21600
	ds_read_b128 v[240:243], v145 offset:26208
	s_waitcnt lgkmcnt(4)
	v_mfma_f32_32x32x16_bf16 v[82:97], v[216:219], v[126:129], v[82:97]
	s_waitcnt lgkmcnt(3)
	v_mfma_f32_32x32x16_bf16 v[98:113], v[220:223], v[122:125], v[98:113]
	s_waitcnt lgkmcnt(2)
	v_mfma_f32_32x32x16_bf16 v[82:97], v[224:227], v[122:125], v[82:97]
	s_waitcnt lgkmcnt(1)
	v_mfma_f32_32x32x16_bf16 v[98:113], v[186:189], v[118:121], v[98:113]
	s_waitcnt lgkmcnt(0)
	v_mfma_f32_32x32x16_bf16 v[82:97], v[240:243], v[118:121], v[82:97]
	s_nop 10
	v_max_f32_e32 v147, v98, v99
	v_max_f32_e32 v188, v90, v91
	v_max_f32_e32 v186, v106, v107
	v_max3_f32 v187, v82, v83, v84
	v_max3_f32 v188, v188, v92, v93
	v_max3_f32 v147, v147, v100, v101
	v_max3_f32 v186, v186, v108, v109
	v_max3_f32 v187, v187, v85, v86
	v_max3_f32 v188, v188, v94, v95
	v_max3_f32 v147, v147, v102, v103
	v_max3_f32 v186, v186, v110, v111
	v_max3_f32 v187, v187, v87, v88
	v_max3_f32 v188, v188, v96, v97
	v_max3_f32 v147, v147, v104, v105
	v_max3_f32 v186, v186, v112, v113
	v_max3_f32 v187, v187, v89, v188
	v_max3_f32 v147, v147, v186, v187
	v_mov_b32_e32 v186, v147
	s_nop 1
	v_permlane32_swap_b32_e32 v147, v186
	v_max_f32_e32 v147, v147, v186
	v_mul_f32_e32 v147, 0x3e38aa3b, v147
	v_max_f32_e32 v216, v152, v147
	v_sub_f32_e32 v147, v216, v152
	v_cmp_lt_f32_e32 vcc, s34, v147
	s_cbranch_vccz .LBB0_835
	v_sub_f32_e32 v147, v152, v216
	v_exp_f32_e32 v152, v147
	v_xor_b32_e32 v147, 0x80000000, v216
	v_mul_f32_e32 v153, v153, v152
	v_pk_mul_f32 v[64:65], v[64:65], v[152:153] op_sel_hi:[1,0]
	v_pk_mul_f32 v[62:63], v[62:63], v[152:153] op_sel_hi:[1,0]
	v_pk_mul_f32 v[60:61], v[60:61], v[152:153] op_sel_hi:[1,0]
	v_pk_mul_f32 v[58:59], v[58:59], v[152:153] op_sel_hi:[1,0]
	v_pk_mul_f32 v[56:57], v[56:57], v[152:153] op_sel_hi:[1,0]
	v_pk_mul_f32 v[54:55], v[54:55], v[152:153] op_sel_hi:[1,0]
	v_pk_mul_f32 v[52:53], v[52:53], v[152:153] op_sel_hi:[1,0]
	v_pk_mul_f32 v[50:51], v[50:51], v[152:153] op_sel_hi:[1,0]
	v_pk_mul_f32 v[16:17], v[16:17], v[152:153] op_sel_hi:[1,0]
	v_pk_mul_f32 v[14:15], v[14:15], v[152:153] op_sel_hi:[1,0]
	v_pk_mul_f32 v[12:13], v[12:13], v[152:153] op_sel_hi:[1,0]
	v_pk_mul_f32 v[10:11], v[10:11], v[152:153] op_sel_hi:[1,0]
	v_pk_mul_f32 v[8:9], v[8:9], v[152:153] op_sel_hi:[1,0]
	v_pk_mul_f32 v[6:7], v[6:7], v[152:153] op_sel_hi:[1,0]
	v_pk_mul_f32 v[4:5], v[4:5], v[152:153] op_sel_hi:[1,0]
	v_pk_mul_f32 v[2:3], v[2:3], v[152:153] op_sel_hi:[1,0]
	v_mov_b32_e32 v152, v216
	s_branch .LBB0_836

; #define LAS __attribute__((address_space(3)))
; __device__ __forceinline__ unsigned pk2(float lo, float hi) { return pg8::pkbf(lo, hi); }
; __device__ __forceinline__ float fexp2(float x) { return __builtin_amdgcn_exp2f(x); }
; #define SCHED_FENCE() __builtin_amdgcn_sched_barrier(0)
; #define PV_LOAD(dst, i) do { _Pragma("unroll") for (int d = 0; d < ND; ++d) { LAS const unsigned char* vp = vb + (16 * (i)) * VRB + d * 64; dst[2 * d] = tr_read(vp); dst[2 * d + 1] = tr_read(vp + 8 * VRB); } } while (0)
; #define PV_MMA(src, i) do { _Pragma("unroll") for (int d = 0; d < ND; ++d) { const bf16x8 vf = __builtin_shufflevector(src[2 * d], src[2 * d + 1], 0, 1, 2, 3, 4, 5, 6, 7); o[d] = MFMA32(vf, pf[i], o[d]); } } while (0)
; template <int DV, bool MASK>
; __device__ __forceinline__ void attn_softmax(f32x16 (&p)[2], f32x16 (&o)[DV / 32], float& m, float& l, float cs, int hi, int dq) {
;     ...
;     float ls0 = 0.f, ls1 = 0.f, ls2 = 0.f, ls3 = 0.f;
; #pragma unroll
;     for (int kvb = 0; kvb < 2; ++kvb)
; #pragma unroll
;         for (int e = 0; e < 16; e += 4) {
;             const float e0 = fexp2(fmaf(p[kvb][e], cs, -m)), e1 = fexp2(fmaf(p[kvb][e + 1], cs, -m)), e2 = fexp2(fmaf(p[kvb][e + 2], cs, -m)), e3 = fexp2(fmaf(p[kvb][e + 3], cs, -m));
;             p[kvb][e] = e0; p[kvb][e + 1] = e1; p[kvb][e + 2] = e2; p[kvb][e + 3] = e3; ls0 += e0; ls1 += e1; ls2 += e2; ls3 += e3; }
;     l += (ls0 + ls1) + (ls2 + ls3);
; }
; template <int DV, int VRB>
; __device__ __forceinline__ void attn_pv(LAS const unsigned char* Vt, const f32x16 (&p)[2], f32x16 (&o)[DV / 32], int vtb) {
;     constexpr int ND = DV / 32;
;     LAS const unsigned char* vb = Vt + vtb;
;     bf16x8 pf[4];
; #pragma unroll
;     for (int i = 0; i < 4; ++i) { const int kvb = i >> 1, s = i & 1;
;         v4u pw; pw.x = pk2(p[kvb][8 * s + 0], p[kvb][8 * s + 1]); pw.y = pk2(p[kvb][8 * s + 2], p[kvb][8 * s + 3]); pw.z = pk2(p[kvb][8 * s + 4], p[kvb][8 * s + 5]); pw.w = pk2(p[kvb][8 * s + 6], p[kvb][8 * s + 7]);
;         pf[i] = __builtin_bit_cast(bf16x8, pw); }
;     s16x4 va[2 * ND], vbq[2 * ND];
;     ...
;     PV_LOAD(va, 0); SCHED_FENCE();
;     PV_LOAD(vbq, 1); PV_MMA(va, 0); SCHED_FENCE();
;     PV_LOAD(va, 2); PV_MMA(vbq, 1); SCHED_FENCE();
;     PV_LOAD(vbq, 3); PV_MMA(va, 2); SCHED_FENCE();
.LBB0_836:
	v_add_f32_e32 v154, 0, v154
	v_add_f32_e32 v155, 0, v155
	v_add_f32_e32 v162, 0, v162
	v_add_f32_e32 v163, 0, v163
	v_add_f32_e32 v154, v164, v154
	v_add_f32_e32 v155, v166, v155
	v_add_f32_e32 v162, v167, v162
	v_add_f32_e32 v163, v168, v163
	v_add_f32_e32 v154, v169, v154
	v_add_f32_e32 v155, v181, v155
	v_add_f32_e32 v162, v182, v162
	v_add_f32_e32 v163, v183, v163
	v_add_f32_e32 v154, v196, v154
	v_add_f32_e32 v155, v197, v155
	v_add_f32_e32 v162, v198, v162
	v_add_f32_e32 v163, v199, v163
	v_add_f32_e32 v154, v200, v154
	v_add_f32_e32 v155, v201, v155
	v_add_f32_e32 v162, v202, v162
	v_add_f32_e32 v163, v203, v163
	v_add_f32_e32 v154, v204, v154
	v_add_f32_e32 v155, v205, v155
	v_add_f32_e32 v162, v206, v162
	v_add_f32_e32 v163, v207, v163
	v_add_f32_e32 v154, v208, v154
	v_add_f32_e32 v155, v209, v155
	v_add_f32_e32 v162, v210, v162
	v_add_f32_e32 v163, v211, v163
	v_add_f32_e32 v154, v212, v154
	v_add_f32_e32 v155, v213, v155
	v_add_f32_e32 v162, v214, v162
	v_add_f32_e32 v163, v215, v163
	v_add_f32_e32 v154, v154, v155
	v_add_f32_e32 v155, v162, v163
	v_fmamk_f32 v98, v98, 0x3e38aa3b, v147
	v_add_f32_e32 v154, v154, v155
	v_exp_f32_e32 v155, v98
	v_fmamk_f32 v98, v99, 0x3e38aa3b, v147
	v_fmamk_f32 v82, v82, 0x3e38aa3b, v147
	v_exp_f32_e32 v162, v98
	v_fmamk_f32 v98, v100, 0x3e38aa3b, v147
	v_exp_f32_e32 v201, v82
	v_fmamk_f32 v82, v83, 0x3e38aa3b, v147
	v_exp_f32_e32 v163, v98
	v_fmamk_f32 v98, v101, 0x3e38aa3b, v147
	v_exp_f32_e32 v202, v82
	v_fmamk_f32 v82, v84, 0x3e38aa3b, v147
	v_exp_f32_e32 v164, v98
	v_fmamk_f32 v98, v102, 0x3e38aa3b, v147
	v_exp_f32_e32 v203, v82
	v_fmamk_f32 v82, v85, 0x3e38aa3b, v147
	v_exp_f32_e32 v166, v98
	v_fmamk_f32 v98, v103, 0x3e38aa3b, v147
	v_exp_f32_e32 v204, v82
	v_fmamk_f32 v82, v86, 0x3e38aa3b, v147
	v_exp_f32_e32 v167, v98
	v_fmamk_f32 v98, v104, 0x3e38aa3b, v147
	v_exp_f32_e32 v205, v82
	v_fmamk_f32 v82, v87, 0x3e38aa3b, v147
	v_exp_f32_e32 v168, v98
	v_fmamk_f32 v98, v105, 0x3e38aa3b, v147
	v_exp_f32_e32 v206, v82
	v_fmamk_f32 v82, v88, 0x3e38aa3b, v147
	v_exp_f32_e32 v169, v98
	v_fmamk_f32 v98, v106, 0x3e38aa3b, v147
	v_exp_f32_e32 v207, v82
	v_fmamk_f32 v82, v89, 0x3e38aa3b, v147
	v_exp_f32_e32 v181, v98
	v_fmamk_f32 v98, v107, 0x3e38aa3b, v147
	v_exp_f32_e32 v208, v82
	v_fmamk_f32 v82, v90, 0x3e38aa3b, v147
	v_exp_f32_e32 v182, v98
	v_fmamk_f32 v98, v108, 0x3e38aa3b, v147
	v_exp_f32_e32 v209, v82
	v_fmamk_f32 v82, v91, 0x3e38aa3b, v147
	v_exp_f32_e32 v183, v98
	v_fmamk_f32 v98, v109, 0x3e38aa3b, v147
	v_exp_f32_e32 v210, v82
	v_fmamk_f32 v82, v92, 0x3e38aa3b, v147
	v_exp_f32_e32 v196, v98
	v_fmamk_f32 v98, v110, 0x3e38aa3b, v147
	v_exp_f32_e32 v211, v82
	v_fmamk_f32 v82, v93, 0x3e38aa3b, v147
	v_exp_f32_e32 v197, v98
	v_fmamk_f32 v98, v111, 0x3e38aa3b, v147
	v_exp_f32_e32 v212, v82
	v_fmamk_f32 v82, v94, 0x3e38aa3b, v147
	v_exp_f32_e32 v198, v98
	v_fmamk_f32 v98, v112, 0x3e38aa3b, v147
	v_exp_f32_e32 v213, v82
	v_fmamk_f32 v82, v95, 0x3e38aa3b, v147
	v_exp_f32_e32 v199, v98
	v_fmamk_f32 v98, v113, 0x3e38aa3b, v147
	v_exp_f32_e32 v214, v82
	v_fmamk_f32 v82, v96, 0x3e38aa3b, v147
	v_exp_f32_e32 v200, v98
	v_exp_f32_e32 v215, v82
	v_fmamk_f32 v82, v97, 0x3e38aa3b, v147
	ds_read_b64_tr_b16 v[94:95], v179 offset:30720
	ds_read_b64_tr_b16 v[96:97], v179 offset:32256
	ds_read_b64_tr_b16 v[100:101], v179 offset:32320
	ds_read_b64_tr_b16 v[98:99], v179 offset:30784
	v_exp_f32_e32 v216, v82
	v_cndmask_b32_e64 v150, v150, 1.0, s[2:3]
	v_fmac_f32_e32 v154, v170, v150
	v_cvt_pk_bf16_f32 v82, v155, v162
	v_cvt_pk_bf16_f32 v83, v163, v164
	v_cvt_pk_bf16_f32 v84, v166, v167
	v_cvt_pk_bf16_f32 v85, v168, v169
	v_cvt_pk_bf16_f32 v86, v181, v182
	v_cvt_pk_bf16_f32 v87, v183, v196
	v_cvt_pk_bf16_f32 v88, v197, v198
	v_cvt_pk_bf16_f32 v89, v199, v200
	v_cvt_pk_bf16_f32 v90, v201, v202
	v_cvt_pk_bf16_f32 v91, v203, v204
	v_cvt_pk_bf16_f32 v92, v205, v206
	v_cvt_pk_bf16_f32 v93, v207, v208
	v_cvt_pk_bf16_f32 v102, v209, v210
	v_cvt_pk_bf16_f32 v103, v211, v212
	v_cvt_pk_bf16_f32 v104, v213, v214
	v_cvt_pk_bf16_f32 v105, v215, v216
	s_waitcnt lgkmcnt(2)
; #define LAS __attribute__((address_space(3)))
; template <int DQK, int KSB>
; __device__ __forceinline__ void attn_scores(LAS const unsigned char* Kt, const bf16x8 (&qf)[DQK / 16], f32x16 (&p)[2], int r32, int hi) {
;     constexpr int NK = DQK / 16;
;     LAS const unsigned char* kp = Kt + r32 * KSB + hi * 16;
;     f32x16 p0, p1;
; #pragma unroll
;     for (int e = 0; e < 16; ++e) { p0[e] = 0.f; p1[e] = 0.f; }
;     bf16x8 kr[3][2];
;     ...
;     QK_LOAD(0); QK_LOAD(1); SCHED_FENCE();
; #pragma unroll
;     for (int ks = 0; ks < NK; ++ks) {
;         if (ks + 2 < NK) QK_LOAD(ks + 2);
;         p0 = MFMA32(kr[ks % 3][0], qf[ks], p0); p1 = MFMA32(kr[ks % 3][1], qf[ks], p1); SCHED_FENCE();
;     }
;     ...
;     p[0] = p0; p[1] = p1;
; }
; template <int DV, bool MASK>
; __device__ __forceinline__ void attn_softmax(f32x16 (&p)[2], f32x16 (&o)[DV / 32], float& m, float& l, float cs, int hi, int dq) {
;     if (MASK) { if (__builtin_amdgcn_readfirstlane(dq) != NO_MASK) {
; #pragma unroll
;         for (int kvb = 0; kvb < 2; ++kvb)
; #pragma unroll
;             for (int e = 0; e < 16; ++e) { const int rel = dq + 32 * kvb + (e & 3) + 8 * (e >> 2) + 4 * hi; if (rel > 128 || rel < -128) p[kvb][e] = -INFINITY; } } }
;     float mx;
;     {
;         float a0 = fmaxf(fmaxf(p[0][0], p[0][1]), p[0][2]), a1 = fmaxf(fmaxf(p[0][8], p[0][9]), p[0][10]), a2 = fmaxf(fmaxf(p[1][0], p[1][1]), p[1][2]), a3 = fmaxf(fmaxf(p[1][8], p[1][9]), p[1][10]);
;         a0 = fmaxf(fmaxf(a0, p[0][3]), p[0][4]); a1 = fmaxf(fmaxf(a1, p[0][11]), p[0][12]); a2 = fmaxf(fmaxf(a2, p[1][3]), p[1][4]); a3 = fmaxf(fmaxf(a3, p[1][11]), p[1][12]);
;         a0 = fmaxf(fmaxf(a0, p[0][5]), p[0][6]); a1 = fmaxf(fmaxf(a1, p[0][13]), p[0][14]); a2 = fmaxf(fmaxf(a2, p[1][5]), p[1][6]); a3 = fmaxf(fmaxf(a3, p[1][13]), p[1][14]);
;         a0 = fmaxf(a0, p[0][7]); a1 = fmaxf(a1, p[0][15]); a2 = fmaxf(a2, p[1][7]); a3 = fmaxf(a3, p[1][15]);
;         mx = fmaxf(fmaxf(a0, a1), fmaxf(a2, a3));
; template <int DV, int VRB>
; __device__ __forceinline__ void attn_pv(LAS const unsigned char* Vt, const f32x16 (&p)[2], f32x16 (&o)[DV / 32], int vtb) {
;     ...
;     PV_LOAD(va, 0); SCHED_FENCE();
;     PV_LOAD(vbq, 1); PV_MMA(va, 0); SCHED_FENCE();
;     PV_LOAD(va, 2); PV_MMA(vbq, 1); SCHED_FENCE();
;     PV_LOAD(vbq, 3); PV_MMA(va, 2); SCHED_FENCE();
;     PV_MMA(vbq, 3); SCHED_FENCE();
	v_mfma_f32_32x32x16_bf16 v[50:65], v[94:97], v[82:85], v[50:65]
	ds_read_b64_tr_b16 v[94:95], v179 offset:33792
	ds_read_b64_tr_b16 v[96:97], v179 offset:35328
	ds_read_b64_tr_b16 v[108:109], v179 offset:35392
	ds_read_b64_tr_b16 v[106:107], v179 offset:33856
	s_waitcnt lgkmcnt(4)
	v_mfma_f32_32x32x16_bf16 v[2:17], v[98:101], v[82:85], v[2:17]
	s_waitcnt lgkmcnt(2)
	v_mfma_f32_32x32x16_bf16 v[50:65], v[94:97], v[86:89], v[50:65]
	ds_read_b64_tr_b16 v[82:83], v179 offset:36864
	ds_read_b64_tr_b16 v[84:85], v179 offset:38400
	ds_read_b64_tr_b16 v[96:97], v179 offset:38464
	ds_read_b64_tr_b16 v[94:95], v179 offset:36928
	s_waitcnt lgkmcnt(4)
	v_mfma_f32_32x32x16_bf16 v[2:17], v[106:109], v[86:89], v[2:17]
	s_waitcnt lgkmcnt(2)
	v_mfma_f32_32x32x16_bf16 v[50:65], v[82:85], v[90:93], v[50:65]
	ds_read_b64_tr_b16 v[82:83], v179 offset:39936
	ds_read_b64_tr_b16 v[84:85], v179 offset:41472
	ds_read_b64_tr_b16 v[88:89], v179 offset:41536
	ds_read_b64_tr_b16 v[86:87], v179 offset:40000
	s_waitcnt lgkmcnt(4)
	v_mfma_f32_32x32x16_bf16 v[2:17], v[94:97], v[90:93], v[2:17]
	s_waitcnt lgkmcnt(2)
	v_mfma_f32_32x32x16_bf16 v[50:65], v[82:85], v[102:105], v[50:65]
	s_waitcnt lgkmcnt(0)
	v_mfma_f32_32x32x16_bf16 v[2:17], v[86:89], v[102:105], v[2:17]
	ds_read_b128 v[82:85], v145 offset:21504
	ds_read_b128 v[186:189], v145 offset:21536
	ds_read_b128 v[86:89], v145 offset:26112
	ds_read_b128 v[218:221], v145 offset:26144
	s_waitcnt lgkmcnt(3)
	v_mfma_f32_32x32x16_bf16 v[98:113], v[82:85], v[114:117], 0
	ds_read_b128 v[222:225], v145 offset:21568
	ds_read_b128 v[226:229], v145 offset:26176
	s_waitcnt lgkmcnt(3)
	v_mfma_f32_32x32x16_bf16 v[82:97], v[86:89], v[114:117], 0
	v_mfma_f32_32x32x16_bf16 v[98:113], v[186:189], v[26:29], v[98:113]
	ds_read_b128 v[186:189], v145 offset:21600
	ds_read_b128 v[240:243], v145 offset:26208
	s_waitcnt lgkmcnt(4)
	v_mfma_f32_32x32x16_bf16 v[82:97], v[218:221], v[26:29], v[82:97]
	s_waitcnt lgkmcnt(3)
	v_mfma_f32_32x32x16_bf16 v[98:113], v[222:225], v[22:25], v[98:113]
	s_waitcnt lgkmcnt(2)
	v_mfma_f32_32x32x16_bf16 v[82:97], v[226:229], v[22:25], v[82:97]
	s_waitcnt lgkmcnt(1)
	v_mfma_f32_32x32x16_bf16 v[98:113], v[186:189], v[18:21], v[98:113]
	s_waitcnt lgkmcnt(0)
	v_mfma_f32_32x32x16_bf16 v[82:97], v[240:243], v[18:21], v[82:97]
	s_nop 10
	v_max_f32_e32 v150, v98, v99
	v_max_f32_e32 v188, v90, v91
	v_max_f32_e32 v186, v106, v107
	v_max3_f32 v187, v82, v83, v84
	v_max3_f32 v188, v188, v92, v93
	v_max3_f32 v150, v150, v100, v101
	v_max3_f32 v186, v186, v108, v109
	v_max3_f32 v187, v187, v85, v86
	v_max3_f32 v188, v188, v94, v95
	v_max3_f32 v150, v150, v102, v103
	v_max3_f32 v186, v186, v110, v111
	v_max3_f32 v187, v187, v87, v88
	v_max3_f32 v188, v188, v96, v97
	v_max3_f32 v150, v150, v104, v105
	v_max3_f32 v186, v186, v112, v113
	v_max3_f32 v187, v187, v89, v188
	v_max3_f32 v150, v150, v186, v187
	v_mov_b32_e32 v186, v150
	s_nop 1
	v_permlane32_swap_b32_e32 v150, v186
	v_max_f32_e32 v150, v150, v186
	v_mul_f32_e32 v150, 0x3e38aa3b, v150
	v_max_f32_e32 v217, v151, v150
	v_sub_f32_e32 v150, v217, v151
	v_cmp_lt_f32_e32 vcc, s34, v150
	s_cbranch_vccz .LBB0_838
	v_sub_f32_e32 v150, v151, v217
	v_exp_f32_e32 v150, v150
	s_nop 0
	v_mul_f32_e32 v154, v154, v150
	v_pk_mul_f32 v[80:81], v[80:81], v[150:151] op_sel_hi:[1,0]
	v_pk_mul_f32 v[78:79], v[78:79], v[150:151] op_sel_hi:[1,0]
	v_pk_mul_f32 v[76:77], v[76:77], v[150:151] op_sel_hi:[1,0]
	v_pk_mul_f32 v[74:75], v[74:75], v[150:151] op_sel_hi:[1,0]
	v_pk_mul_f32 v[72:73], v[72:73], v[150:151] op_sel_hi:[1,0]
	v_pk_mul_f32 v[70:71], v[70:71], v[150:151] op_sel_hi:[1,0]
	v_pk_mul_f32 v[68:69], v[68:69], v[150:151] op_sel_hi:[1,0]
	v_pk_mul_f32 v[66:67], v[66:67], v[150:151] op_sel_hi:[1,0]
	v_pk_mul_f32 v[48:49], v[48:49], v[150:151] op_sel_hi:[1,0]
	v_pk_mul_f32 v[46:47], v[46:47], v[150:151] op_sel_hi:[1,0]
	v_pk_mul_f32 v[44:45], v[44:45], v[150:151] op_sel_hi:[1,0]
	v_pk_mul_f32 v[42:43], v[42:43], v[150:151] op_sel_hi:[1,0]
	v_pk_mul_f32 v[40:41], v[40:41], v[150:151] op_sel_hi:[1,0]
	v_pk_mul_f32 v[38:39], v[38:39], v[150:151] op_sel_hi:[1,0]
	v_pk_mul_f32 v[36:37], v[36:37], v[150:151] op_sel_hi:[1,0]
	v_pk_mul_f32 v[34:35], v[34:35], v[150:151] op_sel_hi:[1,0]
	v_xor_b32_e32 v150, 0x80000000, v217
	v_mov_b32_e32 v151, v217
	s_branch .LBB0_839

; #define LAS __attribute__((address_space(3)))
; __device__ __forceinline__ unsigned pk2(float lo, float hi) { return pg8::pkbf(lo, hi); }
; __device__ __forceinline__ float fexp2(float x) { return __builtin_amdgcn_exp2f(x); }
; #define SCHED_FENCE() __builtin_amdgcn_sched_barrier(0)
; #define PV_LOAD(dst, i) do { _Pragma("unroll") for (int d = 0; d < ND; ++d) { LAS const unsigned char* vp = vb + (16 * (i)) * VRB + d * 64; dst[2 * d] = tr_read(vp); dst[2 * d + 1] = tr_read(vp + 8 * VRB); } } while (0)
; template <int DV, bool MASK>
; __device__ __forceinline__ void attn_softmax(f32x16 (&p)[2], f32x16 (&o)[DV / 32], float& m, float& l, float cs, int hi, int dq) {
;     ...
;     float ls0 = 0.f, ls1 = 0.f, ls2 = 0.f, ls3 = 0.f;
; #pragma unroll
;     for (int kvb = 0; kvb < 2; ++kvb)
; #pragma unroll
;         for (int e = 0; e < 16; e += 4) {
;             const float e0 = fexp2(fmaf(p[kvb][e], cs, -m)), e1 = fexp2(fmaf(p[kvb][e + 1], cs, -m)), e2 = fexp2(fmaf(p[kvb][e + 2], cs, -m)), e3 = fexp2(fmaf(p[kvb][e + 3], cs, -m));
;             p[kvb][e] = e0; p[kvb][e + 1] = e1; p[kvb][e + 2] = e2; p[kvb][e + 3] = e3; ls0 += e0; ls1 += e1; ls2 += e2; ls3 += e3; }
;     l += (ls0 + ls1) + (ls2 + ls3);
; }
; template <int DV, int VRB>
; __device__ __forceinline__ void attn_pv(LAS const unsigned char* Vt, const f32x16 (&p)[2], f32x16 (&o)[DV / 32], int vtb) {
;     constexpr int ND = DV / 32;
;     LAS const unsigned char* vb = Vt + vtb;
;     bf16x8 pf[4];
; #pragma unroll
;     for (int i = 0; i < 4; ++i) { const int kvb = i >> 1, s = i & 1;
;         v4u pw; pw.x = pk2(p[kvb][8 * s + 0], p[kvb][8 * s + 1]); pw.y = pk2(p[kvb][8 * s + 2], p[kvb][8 * s + 3]); pw.z = pk2(p[kvb][8 * s + 4], p[kvb][8 * s + 5]); pw.w = pk2(p[kvb][8 * s + 6], p[kvb][8 * s + 7]);
;         pf[i] = __builtin_bit_cast(bf16x8, pw); }
;     s16x4 va[2 * ND], vbq[2 * ND];
;     ...
;     PV_LOAD(va, 0); SCHED_FENCE();
;     PV_LOAD(vbq, 1); PV_MMA(va, 0); SCHED_FENCE();
;     PV_LOAD(va, 2); PV_MMA(vbq, 1); SCHED_FENCE();
;     PV_LOAD(vbq, 3); PV_MMA(va, 2); SCHED_FENCE();
;     PV_MMA(vbq, 3); SCHED_FENCE();
; __device__ __forceinline__ void swa_unit(const bf16* Z, const float* sink  , bf16* Y, int b, int g, int blk, int cblk, LAS unsigned char* L, int tid) {
;     ...
;         if (more) SWA_STORE((t + 1) & 1);
;         __syncthreads();
.LBB0_839:
	v_add_f32_e32 v155, 0, v155
	v_add_f32_e32 v162, 0, v162
	v_add_f32_e32 v163, 0, v163
	v_add_f32_e32 v164, 0, v164
	v_add_f32_e32 v155, v166, v155
	v_add_f32_e32 v162, v167, v162
	v_add_f32_e32 v163, v168, v163
	v_add_f32_e32 v164, v169, v164
	v_add_f32_e32 v155, v181, v155
	v_add_f32_e32 v162, v182, v162
	v_add_f32_e32 v163, v183, v163
	v_add_f32_e32 v164, v196, v164
	v_add_f32_e32 v155, v197, v155
	v_add_f32_e32 v162, v198, v162
	v_add_f32_e32 v163, v199, v163
	v_add_f32_e32 v164, v200, v164
	v_add_f32_e32 v155, v201, v155
	v_add_f32_e32 v162, v202, v162
	v_add_f32_e32 v163, v203, v163
	v_add_f32_e32 v164, v204, v164
	v_add_f32_e32 v155, v205, v155
	v_add_f32_e32 v162, v206, v162
	v_add_f32_e32 v163, v207, v163
	v_add_f32_e32 v164, v208, v164
	v_add_f32_e32 v155, v209, v155
	v_add_f32_e32 v162, v210, v162
	v_add_f32_e32 v163, v211, v163
	v_add_f32_e32 v164, v212, v164
	v_add_f32_e32 v155, v213, v155
	v_add_f32_e32 v162, v214, v162
	v_add_f32_e32 v163, v215, v163
	v_add_f32_e32 v164, v216, v164
	v_add_f32_e32 v155, v155, v162
	v_add_f32_e32 v162, v163, v164
	v_add_f32_e32 v155, v155, v162
	v_fmamk_f32 v98, v98, 0x3e38aa3b, v150
	v_add_f32_e32 v153, v153, v155
	v_exp_f32_e32 v155, v98
	v_fmamk_f32 v98, v99, 0x3e38aa3b, v150
	v_fmamk_f32 v82, v82, 0x3e38aa3b, v150
	v_exp_f32_e32 v162, v98
	v_fmamk_f32 v98, v100, 0x3e38aa3b, v150
	v_exp_f32_e32 v201, v82
	v_fmamk_f32 v82, v83, 0x3e38aa3b, v150
	v_exp_f32_e32 v163, v98
	v_fmamk_f32 v98, v101, 0x3e38aa3b, v150
	v_exp_f32_e32 v202, v82
	v_fmamk_f32 v82, v84, 0x3e38aa3b, v150
	v_exp_f32_e32 v164, v98
	v_fmamk_f32 v98, v102, 0x3e38aa3b, v150
	v_exp_f32_e32 v203, v82
	v_fmamk_f32 v82, v85, 0x3e38aa3b, v150
	v_exp_f32_e32 v166, v98
	v_fmamk_f32 v98, v103, 0x3e38aa3b, v150
	v_exp_f32_e32 v204, v82
	v_fmamk_f32 v82, v86, 0x3e38aa3b, v150
	v_exp_f32_e32 v167, v98
	v_fmamk_f32 v98, v104, 0x3e38aa3b, v150
	v_exp_f32_e32 v205, v82
	v_fmamk_f32 v82, v87, 0x3e38aa3b, v150
	v_exp_f32_e32 v168, v98
	v_fmamk_f32 v98, v105, 0x3e38aa3b, v150
	v_exp_f32_e32 v206, v82
	v_fmamk_f32 v82, v88, 0x3e38aa3b, v150
	v_exp_f32_e32 v169, v98
	v_fmamk_f32 v98, v106, 0x3e38aa3b, v150
	v_exp_f32_e32 v207, v82
	v_fmamk_f32 v82, v89, 0x3e38aa3b, v150
	v_exp_f32_e32 v181, v98
	v_fmamk_f32 v98, v107, 0x3e38aa3b, v150
	v_exp_f32_e32 v208, v82
	v_fmamk_f32 v82, v90, 0x3e38aa3b, v150
	v_exp_f32_e32 v182, v98
	v_fmamk_f32 v98, v108, 0x3e38aa3b, v150
	v_exp_f32_e32 v209, v82
	v_fmamk_f32 v82, v91, 0x3e38aa3b, v150
	v_exp_f32_e32 v183, v98
	v_fmamk_f32 v98, v109, 0x3e38aa3b, v150
	v_exp_f32_e32 v210, v82
	v_fmamk_f32 v82, v92, 0x3e38aa3b, v150
	v_exp_f32_e32 v196, v98
	v_fmamk_f32 v98, v110, 0x3e38aa3b, v150
	v_exp_f32_e32 v211, v82
	v_fmamk_f32 v82, v93, 0x3e38aa3b, v150
	v_exp_f32_e32 v197, v98
	v_fmamk_f32 v98, v111, 0x3e38aa3b, v150
	v_exp_f32_e32 v212, v82
	v_fmamk_f32 v82, v94, 0x3e38aa3b, v150
	v_exp_f32_e32 v198, v98
	v_fmamk_f32 v98, v112, 0x3e38aa3b, v150
	v_exp_f32_e32 v213, v82
	v_fmamk_f32 v82, v95, 0x3e38aa3b, v150
	v_exp_f32_e32 v199, v98
	v_fmamk_f32 v98, v113, 0x3e38aa3b, v150
	v_exp_f32_e32 v214, v82
	v_fmamk_f32 v82, v96, 0x3e38aa3b, v150
	v_exp_f32_e32 v200, v98
	v_exp_f32_e32 v215, v82
	v_fmamk_f32 v82, v97, 0x3e38aa3b, v150
	ds_read_b64_tr_b16 v[94:95], v179 offset:30720
	ds_read_b64_tr_b16 v[96:97], v179 offset:32256
	ds_read_b64_tr_b16 v[100:101], v179 offset:32320
	ds_read_b64_tr_b16 v[98:99], v179 offset:30784
	v_exp_f32_e32 v216, v82
	v_cvt_pk_bf16_f32 v82, v155, v162
	v_cvt_pk_bf16_f32 v83, v163, v164
	v_cvt_pk_bf16_f32 v84, v166, v167
	v_cvt_pk_bf16_f32 v85, v168, v169
	v_cvt_pk_bf16_f32 v86, v181, v182
	v_cvt_pk_bf16_f32 v87, v183, v196
	v_cvt_pk_bf16_f32 v88, v197, v198
	v_cvt_pk_bf16_f32 v89, v199, v200
	v_cvt_pk_bf16_f32 v90, v201, v202
	v_cvt_pk_bf16_f32 v91, v203, v204
	v_cvt_pk_bf16_f32 v92, v205, v206
	v_cvt_pk_bf16_f32 v93, v207, v208
	v_cvt_pk_bf16_f32 v102, v209, v210
	v_cvt_pk_bf16_f32 v103, v211, v212
	v_cvt_pk_bf16_f32 v104, v213, v214
	v_cvt_pk_bf16_f32 v105, v215, v216
	s_waitcnt lgkmcnt(2)
	v_mfma_f32_32x32x16_bf16 v[66:81], v[94:97], v[82:85], v[66:81]
	ds_read_b64_tr_b16 v[94:95], v179 offset:33792
	ds_read_b64_tr_b16 v[96:97], v179 offset:35328
	ds_read_b64_tr_b16 v[108:109], v179 offset:35392
	ds_read_b64_tr_b16 v[106:107], v179 offset:33856
	s_waitcnt lgkmcnt(4)
	v_mfma_f32_32x32x16_bf16 v[34:49], v[98:101], v[82:85], v[34:49]
	s_waitcnt lgkmcnt(2)
	v_mfma_f32_32x32x16_bf16 v[66:81], v[94:97], v[86:89], v[66:81]
	ds_read_b64_tr_b16 v[82:83], v179 offset:36864
	ds_read_b64_tr_b16 v[84:85], v179 offset:38400
	ds_read_b64_tr_b16 v[96:97], v179 offset:38464
	ds_read_b64_tr_b16 v[94:95], v179 offset:36928
	s_waitcnt lgkmcnt(4)
	v_mfma_f32_32x32x16_bf16 v[34:49], v[106:109], v[86:89], v[34:49]
	s_waitcnt lgkmcnt(2)
	v_mfma_f32_32x32x16_bf16 v[66:81], v[82:85], v[90:93], v[66:81]
	ds_read_b64_tr_b16 v[82:83], v179 offset:39936
	ds_read_b64_tr_b16 v[84:85], v179 offset:41472
	ds_read_b64_tr_b16 v[88:89], v179 offset:41536
	ds_read_b64_tr_b16 v[86:87], v179 offset:40000
	s_waitcnt lgkmcnt(4)
	v_mfma_f32_32x32x16_bf16 v[34:49], v[94:97], v[90:93], v[34:49]
	s_waitcnt lgkmcnt(2)
	v_mfma_f32_32x32x16_bf16 v[66:81], v[82:85], v[102:105], v[66:81]
	s_waitcnt lgkmcnt(0)
	v_mfma_f32_32x32x16_bf16 v[34:49], v[86:89], v[102:105], v[34:49]
	s_mov_b32 s2, 0x168000
	v_add_co_u32_e32 v82, vcc, s2, v148
	s_waitcnt vmcnt(1)
	ds_write_b128 v174, v[134:137]
	s_waitcnt vmcnt(0)
	ds_write_b128 v165, v[138:141] offset:9216
	v_addc_co_u32_e32 v83, vcc, 0, v149, vcc
	s_waitcnt lgkmcnt(0)
	s_barrier
; #define LAS __attribute__((address_space(3)))
; #define SCHED_FENCE() __builtin_amdgcn_sched_barrier(0)
; template <int DQK, int KSB>
; __device__ __forceinline__ void attn_scores(LAS const unsigned char* Kt, const bf16x8 (&qf)[DQK / 16], f32x16 (&p)[2], int r32, int hi) {
;     constexpr int NK = DQK / 16;
;     LAS const unsigned char* kp = Kt + r32 * KSB + hi * 16;
;     f32x16 p0, p1;
; #pragma unroll
;     for (int e = 0; e < 16; ++e) { p0[e] = 0.f; p1[e] = 0.f; }
;     bf16x8 kr[3][2];
;     ...
;     QK_LOAD(0); QK_LOAD(1); SCHED_FENCE();
; #pragma unroll
;     for (int ks = 0; ks < NK; ++ks) {
;         if (ks + 2 < NK) QK_LOAD(ks + 2);
;         p0 = MFMA32(kr[ks % 3][0], qf[ks], p0); p1 = MFMA32(kr[ks % 3][1], qf[ks], p1); SCHED_FENCE();
;     }
;     ...
;     p[0] = p0; p[1] = p1;
; }
; template <int DV, bool MASK>
; __device__ __forceinline__ void attn_softmax(f32x16 (&p)[2], f32x16 (&o)[DV / 32], float& m, float& l, float cs, int hi, int dq) {
;     if (MASK) { if (__builtin_amdgcn_readfirstlane(dq) != NO_MASK) {
; #pragma unroll
;         for (int kvb = 0; kvb < 2; ++kvb)
; #pragma unroll
;             for (int e = 0; e < 16; ++e) { const int rel = dq + 32 * kvb + (e & 3) + 8 * (e >> 2) + 4 * hi; if (rel > 128 || rel < -128) p[kvb][e] = -INFINITY; } } }
;     float mx;
;     {
;         float a0 = fmaxf(fmaxf(p[0][0], p[0][1]), p[0][2]), a1 = fmaxf(fmaxf(p[0][8], p[0][9]), p[0][10]), a2 = fmaxf(fmaxf(p[1][0], p[1][1]), p[1][2]), a3 = fmaxf(fmaxf(p[1][8], p[1][9]), p[1][10]);
;         a0 = fmaxf(fmaxf(a0, p[0][3]), p[0][4]); a1 = fmaxf(fmaxf(a1, p[0][11]), p[0][12]); a2 = fmaxf(fmaxf(a2, p[1][3]), p[1][4]); a3 = fmaxf(fmaxf(a3, p[1][11]), p[1][12]);
; __device__ __forceinline__ void swa_unit(const bf16* Z, const float* sink  , bf16* Y, int b, int g, int blk, int cblk, LAS unsigned char* L, int tid) {
;     ...
;     for (int t = 0; t < ntiles; ++t) {
;         const bool more = t + 1 < ntiles;
;         if (more) SWA_LOAD(t + 1);
;         LAS const unsigned char* Kt = L + (t & 1) * SWA_BUF;
;         const int kpos0 = 64 * (wlo + t - 4);
;         const bool edge = t >= 4 && (wlo + t - 4 == blk - 2 || wlo + t - 4 == blk + 2);
; #pragma unroll
;         for (int sb = 0; sb < 2; ++sb) attn_tile<64, 64, SWA_KSB, SWA_VRB, true>(Kt, Kt + SWA_KT, qf[sb], o[sb], m[sb], l[sb], cs, r32, hi, vtb, edge ? kpos0 - (64 * blk + 32 * sb + r32) : NO_MASK);
	global_load_dwordx4 v[134:137], v[82:83], off
	global_load_dwordx4 v[138:141], v[82:83], off offset:256
	ds_read_b128 v[82:85], v145
	ds_read_b128 v[186:189], v145 offset:32
	ds_read_b128 v[86:89], v145 offset:4608
	ds_read_b128 v[218:221], v145 offset:4640
	s_waitcnt lgkmcnt(3)
	v_mfma_f32_32x32x16_bf16 v[98:113], v[82:85], v[130:133], 0
	ds_read_b128 v[222:225], v145 offset:64
	ds_read_b128 v[226:229], v145 offset:4672
	s_waitcnt lgkmcnt(3)
	v_mfma_f32_32x32x16_bf16 v[82:97], v[86:89], v[130:133], 0
	v_mfma_f32_32x32x16_bf16 v[98:113], v[186:189], v[126:129], v[98:113]
	ds_read_b128 v[186:189], v145 offset:96
	ds_read_b128 v[240:243], v145 offset:4704
	s_waitcnt lgkmcnt(4)
	v_mfma_f32_32x32x16_bf16 v[82:97], v[218:221], v[126:129], v[82:97]
	s_waitcnt lgkmcnt(3)
	v_mfma_f32_32x32x16_bf16 v[98:113], v[222:225], v[122:125], v[98:113]
	s_waitcnt lgkmcnt(2)
	v_mfma_f32_32x32x16_bf16 v[82:97], v[226:229], v[122:125], v[82:97]
	s_waitcnt lgkmcnt(1)
	v_mfma_f32_32x32x16_bf16 v[98:113], v[186:189], v[118:121], v[98:113]
	s_waitcnt lgkmcnt(0)
	v_mfma_f32_32x32x16_bf16 v[82:97], v[240:243], v[118:121], v[82:97]
	s_nop 10
	v_max_f32_e32 v148, v98, v99
	v_max_f32_e32 v187, v90, v91
	v_max_f32_e32 v149, v106, v107
	v_max3_f32 v186, v82, v83, v84
	v_max3_f32 v187, v187, v92, v93
	v_max3_f32 v148, v148, v100, v101
	v_max3_f32 v149, v149, v108, v109
	v_max3_f32 v186, v186, v85, v86
	v_max3_f32 v187, v187, v94, v95
	v_max3_f32 v148, v148, v102, v103
	v_max3_f32 v149, v149, v110, v111
	v_max3_f32 v186, v186, v87, v88
	v_max3_f32 v187, v187, v96, v97
	v_max3_f32 v148, v148, v104, v105
	v_max3_f32 v149, v149, v112, v113
	v_max3_f32 v186, v186, v89, v187
	v_max3_f32 v148, v148, v149, v186
	v_mov_b32_e32 v149, v148
	s_nop 1
	v_permlane32_swap_b32_e32 v148, v149
	v_max_f32_e32 v148, v148, v149
	v_mul_f32_e32 v148, 0x3e38aa3b, v148
	v_max_f32_e32 v148, v152, v148
	v_sub_f32_e32 v149, v148, v152
	v_cmp_lt_f32_e32 vcc, s34, v149
	s_cbranch_vccz .LBB0_841
	v_sub_f32_e32 v147, v152, v148
	v_exp_f32_e32 v152, v147
	v_xor_b32_e32 v147, 0x80000000, v148
	v_mul_f32_e32 v153, v153, v152
	v_pk_mul_f32 v[64:65], v[64:65], v[152:153] op_sel_hi:[1,0]
	v_pk_mul_f32 v[62:63], v[62:63], v[152:153] op_sel_hi:[1,0]
	v_pk_mul_f32 v[60:61], v[60:61], v[152:153] op_sel_hi:[1,0]
	v_pk_mul_f32 v[58:59], v[58:59], v[152:153] op_sel_hi:[1,0]
	v_pk_mul_f32 v[56:57], v[56:57], v[152:153] op_sel_hi:[1,0]
	v_pk_mul_f32 v[54:55], v[54:55], v[152:153] op_sel_hi:[1,0]
	v_pk_mul_f32 v[52:53], v[52:53], v[152:153] op_sel_hi:[1,0]
	v_pk_mul_f32 v[50:51], v[50:51], v[152:153] op_sel_hi:[1,0]
	v_pk_mul_f32 v[16:17], v[16:17], v[152:153] op_sel_hi:[1,0]
	v_pk_mul_f32 v[14:15], v[14:15], v[152:153] op_sel_hi:[1,0]
	v_pk_mul_f32 v[12:13], v[12:13], v[152:153] op_sel_hi:[1,0]
	v_pk_mul_f32 v[10:11], v[10:11], v[152:153] op_sel_hi:[1,0]
	v_pk_mul_f32 v[8:9], v[8:9], v[152:153] op_sel_hi:[1,0]
	v_pk_mul_f32 v[6:7], v[6:7], v[152:153] op_sel_hi:[1,0]
	v_pk_mul_f32 v[4:5], v[4:5], v[152:153] op_sel_hi:[1,0]
	v_pk_mul_f32 v[2:3], v[2:3], v[152:153] op_sel_hi:[1,0]
	s_branch .LBB0_842

; #define LAS __attribute__((address_space(3)))
; __device__ __forceinline__ unsigned pk2(float lo, float hi) { return pg8::pkbf(lo, hi); }
; __device__ __forceinline__ float fexp2(float x) { return __builtin_amdgcn_exp2f(x); }
; #define SCHED_FENCE() __builtin_amdgcn_sched_barrier(0)
; #define PV_LOAD(dst, i) do { _Pragma("unroll") for (int d = 0; d < ND; ++d) { LAS const unsigned char* vp = vb + (16 * (i)) * VRB + d * 64; dst[2 * d] = tr_read(vp); dst[2 * d + 1] = tr_read(vp + 8 * VRB); } } while (0)
; #define PV_MMA(src, i) do { _Pragma("unroll") for (int d = 0; d < ND; ++d) { const bf16x8 vf = __builtin_shufflevector(src[2 * d], src[2 * d + 1], 0, 1, 2, 3, 4, 5, 6, 7); o[d] = MFMA32(vf, pf[i], o[d]); } } while (0)
; template <int DV, bool MASK>
; __device__ __forceinline__ void attn_softmax(f32x16 (&p)[2], f32x16 (&o)[DV / 32], float& m, float& l, float cs, int hi, int dq) {
;     ...
;     float ls0 = 0.f, ls1 = 0.f, ls2 = 0.f, ls3 = 0.f;
; #pragma unroll
;     for (int kvb = 0; kvb < 2; ++kvb)
; #pragma unroll
;         for (int e = 0; e < 16; e += 4) {
;             const float e0 = fexp2(fmaf(p[kvb][e], cs, -m)), e1 = fexp2(fmaf(p[kvb][e + 1], cs, -m)), e2 = fexp2(fmaf(p[kvb][e + 2], cs, -m)), e3 = fexp2(fmaf(p[kvb][e + 3], cs, -m));
;             p[kvb][e] = e0; p[kvb][e + 1] = e1; p[kvb][e + 2] = e2; p[kvb][e + 3] = e3; ls0 += e0; ls1 += e1; ls2 += e2; ls3 += e3; }
;     l += (ls0 + ls1) + (ls2 + ls3);
; }
; template <int DV, int VRB>
; __device__ __forceinline__ void attn_pv(LAS const unsigned char* Vt, const f32x16 (&p)[2], f32x16 (&o)[DV / 32], int vtb) {
;     constexpr int ND = DV / 32;
;     LAS const unsigned char* vb = Vt + vtb;
;     bf16x8 pf[4];
; #pragma unroll
;     for (int i = 0; i < 4; ++i) { const int kvb = i >> 1, s = i & 1;
;         v4u pw; pw.x = pk2(p[kvb][8 * s + 0], p[kvb][8 * s + 1]); pw.y = pk2(p[kvb][8 * s + 2], p[kvb][8 * s + 3]); pw.z = pk2(p[kvb][8 * s + 4], p[kvb][8 * s + 5]); pw.w = pk2(p[kvb][8 * s + 6], p[kvb][8 * s + 7]);
;         pf[i] = __builtin_bit_cast(bf16x8, pw); }
;     s16x4 va[2 * ND], vbq[2 * ND];
;     ...
;     PV_LOAD(va, 0); SCHED_FENCE();
;     PV_LOAD(vbq, 1); PV_MMA(va, 0); SCHED_FENCE();
;     PV_LOAD(va, 2); PV_MMA(vbq, 1); SCHED_FENCE();
;     PV_LOAD(vbq, 3); PV_MMA(va, 2); SCHED_FENCE();
.LBB0_842:
	v_add_f32_e32 v149, 0, v155
	v_add_f32_e32 v152, 0, v162
	v_add_f32_e32 v155, 0, v163
	v_add_f32_e32 v162, 0, v164
	v_add_f32_e32 v149, v166, v149
	v_add_f32_e32 v152, v167, v152
	v_add_f32_e32 v155, v168, v155
	v_add_f32_e32 v162, v169, v162
	v_add_f32_e32 v149, v181, v149
	v_add_f32_e32 v152, v182, v152
	v_add_f32_e32 v155, v183, v155
	v_add_f32_e32 v162, v196, v162
	v_add_f32_e32 v149, v197, v149
	v_add_f32_e32 v152, v198, v152
	v_add_f32_e32 v155, v199, v155
	v_add_f32_e32 v162, v200, v162
	v_add_f32_e32 v149, v201, v149
	v_add_f32_e32 v152, v202, v152
	v_add_f32_e32 v155, v203, v155
	v_add_f32_e32 v162, v204, v162
	v_add_f32_e32 v149, v205, v149
	v_add_f32_e32 v152, v206, v152
	v_add_f32_e32 v155, v207, v155
	v_add_f32_e32 v162, v208, v162
	v_add_f32_e32 v149, v209, v149
	v_add_f32_e32 v152, v210, v152
	v_add_f32_e32 v155, v211, v155
	v_add_f32_e32 v162, v212, v162
	v_add_f32_e32 v149, v213, v149
	v_add_f32_e32 v152, v214, v152
	v_add_f32_e32 v155, v215, v155
	v_add_f32_e32 v162, v216, v162
	v_add_f32_e32 v149, v149, v152
	v_add_f32_e32 v152, v155, v162
	v_add_f32_e32 v149, v149, v152
	v_fmamk_f32 v98, v98, 0x3e38aa3b, v147
	v_add_f32_e32 v152, v154, v149
	v_exp_f32_e32 v154, v98
	v_fmamk_f32 v98, v99, 0x3e38aa3b, v147
	v_fmamk_f32 v82, v82, 0x3e38aa3b, v147
	v_exp_f32_e32 v155, v98
	v_fmamk_f32 v98, v100, 0x3e38aa3b, v147
	v_exp_f32_e32 v200, v82
	v_fmamk_f32 v82, v83, 0x3e38aa3b, v147
	v_exp_f32_e32 v162, v98
	v_fmamk_f32 v98, v101, 0x3e38aa3b, v147
	v_exp_f32_e32 v201, v82
	v_fmamk_f32 v82, v84, 0x3e38aa3b, v147
	v_exp_f32_e32 v163, v98
	v_fmamk_f32 v98, v102, 0x3e38aa3b, v147
	v_exp_f32_e32 v202, v82
	v_fmamk_f32 v82, v85, 0x3e38aa3b, v147
	v_exp_f32_e32 v164, v98
	v_fmamk_f32 v98, v103, 0x3e38aa3b, v147
	v_exp_f32_e32 v203, v82
	v_fmamk_f32 v82, v86, 0x3e38aa3b, v147
	v_exp_f32_e32 v166, v98
	v_fmamk_f32 v98, v104, 0x3e38aa3b, v147
	v_exp_f32_e32 v204, v82
	v_fmamk_f32 v82, v87, 0x3e38aa3b, v147
	v_exp_f32_e32 v167, v98
	v_fmamk_f32 v98, v105, 0x3e38aa3b, v147
	v_exp_f32_e32 v205, v82
	v_fmamk_f32 v82, v88, 0x3e38aa3b, v147
	v_exp_f32_e32 v168, v98
	v_fmamk_f32 v98, v106, 0x3e38aa3b, v147
	v_exp_f32_e32 v206, v82
	v_fmamk_f32 v82, v89, 0x3e38aa3b, v147
	v_exp_f32_e32 v169, v98
	v_fmamk_f32 v98, v107, 0x3e38aa3b, v147
	v_exp_f32_e32 v207, v82
	v_fmamk_f32 v82, v90, 0x3e38aa3b, v147
	v_exp_f32_e32 v181, v98
	v_fmamk_f32 v98, v108, 0x3e38aa3b, v147
	v_exp_f32_e32 v208, v82
	v_fmamk_f32 v82, v91, 0x3e38aa3b, v147
	v_exp_f32_e32 v182, v98
	v_fmamk_f32 v98, v109, 0x3e38aa3b, v147
	v_exp_f32_e32 v209, v82
	v_fmamk_f32 v82, v92, 0x3e38aa3b, v147
	v_exp_f32_e32 v183, v98
	v_fmamk_f32 v98, v110, 0x3e38aa3b, v147
	v_exp_f32_e32 v210, v82
	v_fmamk_f32 v82, v93, 0x3e38aa3b, v147
	v_exp_f32_e32 v196, v98
	v_fmamk_f32 v98, v111, 0x3e38aa3b, v147
	v_exp_f32_e32 v211, v82
	v_fmamk_f32 v82, v94, 0x3e38aa3b, v147
	v_exp_f32_e32 v197, v98
	v_fmamk_f32 v98, v112, 0x3e38aa3b, v147
	v_exp_f32_e32 v212, v82
	v_fmamk_f32 v82, v95, 0x3e38aa3b, v147
	v_exp_f32_e32 v198, v98
	v_fmamk_f32 v98, v113, 0x3e38aa3b, v147
	v_exp_f32_e32 v213, v82
	v_fmamk_f32 v82, v96, 0x3e38aa3b, v147
	v_exp_f32_e32 v199, v98
	v_exp_f32_e32 v214, v82
	v_fmamk_f32 v82, v97, 0x3e38aa3b, v147
	ds_read_b64_tr_b16 v[94:95], v179 offset:9216
	ds_read_b64_tr_b16 v[96:97], v179 offset:10752
	ds_read_b64_tr_b16 v[100:101], v179 offset:10816
	ds_read_b64_tr_b16 v[98:99], v179 offset:9280
	v_exp_f32_e32 v215, v82
	v_cvt_pk_bf16_f32 v82, v154, v155
	v_cvt_pk_bf16_f32 v83, v162, v163
	v_cvt_pk_bf16_f32 v84, v164, v166
	v_cvt_pk_bf16_f32 v85, v167, v168
	v_cvt_pk_bf16_f32 v86, v169, v181
	v_cvt_pk_bf16_f32 v87, v182, v183
	v_cvt_pk_bf16_f32 v88, v196, v197
	v_cvt_pk_bf16_f32 v89, v198, v199
	v_cvt_pk_bf16_f32 v90, v200, v201
	v_cvt_pk_bf16_f32 v91, v202, v203
	v_cvt_pk_bf16_f32 v92, v204, v205
	v_cvt_pk_bf16_f32 v93, v206, v207
	v_cvt_pk_bf16_f32 v102, v208, v209
	v_cvt_pk_bf16_f32 v103, v210, v211
	v_cvt_pk_bf16_f32 v104, v212, v213
	v_cvt_pk_bf16_f32 v105, v214, v215
	s_waitcnt lgkmcnt(2)
; #define LAS __attribute__((address_space(3)))
; template <int DQK, int KSB>
; __device__ __forceinline__ void attn_scores(LAS const unsigned char* Kt, const bf16x8 (&qf)[DQK / 16], f32x16 (&p)[2], int r32, int hi) {
;     constexpr int NK = DQK / 16;
;     LAS const unsigned char* kp = Kt + r32 * KSB + hi * 16;
;     f32x16 p0, p1;
; #pragma unroll
;     for (int e = 0; e < 16; ++e) { p0[e] = 0.f; p1[e] = 0.f; }
;     bf16x8 kr[3][2];
;     ...
;     QK_LOAD(0); QK_LOAD(1); SCHED_FENCE();
; #pragma unroll
;     for (int ks = 0; ks < NK; ++ks) {
;         if (ks + 2 < NK) QK_LOAD(ks + 2);
;         p0 = MFMA32(kr[ks % 3][0], qf[ks], p0); p1 = MFMA32(kr[ks % 3][1], qf[ks], p1); SCHED_FENCE();
;     }
;     ...
;     p[0] = p0; p[1] = p1;
; }
; template <int DV, bool MASK>
; __device__ __forceinline__ void attn_softmax(f32x16 (&p)[2], f32x16 (&o)[DV / 32], float& m, float& l, float cs, int hi, int dq) {
;     if (MASK) { if (__builtin_amdgcn_readfirstlane(dq) != NO_MASK) {
; #pragma unroll
;         for (int kvb = 0; kvb < 2; ++kvb)
; #pragma unroll
;             for (int e = 0; e < 16; ++e) { const int rel = dq + 32 * kvb + (e & 3) + 8 * (e >> 2) + 4 * hi; if (rel > 128 || rel < -128) p[kvb][e] = -INFINITY; } } }
;     float mx;
;     {
;         float a0 = fmaxf(fmaxf(p[0][0], p[0][1]), p[0][2]), a1 = fmaxf(fmaxf(p[0][8], p[0][9]), p[0][10]), a2 = fmaxf(fmaxf(p[1][0], p[1][1]), p[1][2]), a3 = fmaxf(fmaxf(p[1][8], p[1][9]), p[1][10]);
;         a0 = fmaxf(fmaxf(a0, p[0][3]), p[0][4]); a1 = fmaxf(fmaxf(a1, p[0][11]), p[0][12]); a2 = fmaxf(fmaxf(a2, p[1][3]), p[1][4]); a3 = fmaxf(fmaxf(a3, p[1][11]), p[1][12]);
;         a0 = fmaxf(fmaxf(a0, p[0][5]), p[0][6]); a1 = fmaxf(fmaxf(a1, p[0][13]), p[0][14]); a2 = fmaxf(fmaxf(a2, p[1][5]), p[1][6]); a3 = fmaxf(fmaxf(a3, p[1][13]), p[1][14]);
;         a0 = fmaxf(a0, p[0][7]); a1 = fmaxf(a1, p[0][15]); a2 = fmaxf(a2, p[1][7]); a3 = fmaxf(a3, p[1][15]);
;         mx = fmaxf(fmaxf(a0, a1), fmaxf(a2, a3));
; template <int DV, int VRB>
; __device__ __forceinline__ void attn_pv(LAS const unsigned char* Vt, const f32x16 (&p)[2], f32x16 (&o)[DV / 32], int vtb) {
;     ...
;     PV_LOAD(va, 0); SCHED_FENCE();
;     PV_LOAD(vbq, 1); PV_MMA(va, 0); SCHED_FENCE();
;     PV_LOAD(va, 2); PV_MMA(vbq, 1); SCHED_FENCE();
;     PV_LOAD(vbq, 3); PV_MMA(va, 2); SCHED_FENCE();
;     PV_MMA(vbq, 3); SCHED_FENCE();
	v_mfma_f32_32x32x16_bf16 v[50:65], v[94:97], v[82:85], v[50:65]
	ds_read_b64_tr_b16 v[94:95], v179 offset:12288
	ds_read_b64_tr_b16 v[96:97], v179 offset:13824
	ds_read_b64_tr_b16 v[108:109], v179 offset:13888
	ds_read_b64_tr_b16 v[106:107], v179 offset:12352
	s_waitcnt lgkmcnt(4)
	v_mfma_f32_32x32x16_bf16 v[2:17], v[98:101], v[82:85], v[2:17]
	s_waitcnt lgkmcnt(2)
	v_mfma_f32_32x32x16_bf16 v[50:65], v[94:97], v[86:89], v[50:65]
	ds_read_b64_tr_b16 v[82:83], v179 offset:15360
	ds_read_b64_tr_b16 v[84:85], v179 offset:16896
	ds_read_b64_tr_b16 v[96:97], v179 offset:16960
	ds_read_b64_tr_b16 v[94:95], v179 offset:15424
	s_waitcnt lgkmcnt(4)
	v_mfma_f32_32x32x16_bf16 v[2:17], v[106:109], v[86:89], v[2:17]
	s_waitcnt lgkmcnt(2)
	v_mfma_f32_32x32x16_bf16 v[50:65], v[82:85], v[90:93], v[50:65]
	ds_read_b64_tr_b16 v[82:83], v179 offset:18432
	ds_read_b64_tr_b16 v[84:85], v179 offset:19968
	ds_read_b64_tr_b16 v[88:89], v179 offset:20032
	ds_read_b64_tr_b16 v[86:87], v179 offset:18496
	s_waitcnt lgkmcnt(4)
	v_mfma_f32_32x32x16_bf16 v[2:17], v[94:97], v[90:93], v[2:17]
	s_waitcnt lgkmcnt(2)
	v_mfma_f32_32x32x16_bf16 v[50:65], v[82:85], v[102:105], v[50:65]
	s_waitcnt lgkmcnt(0)
	v_mfma_f32_32x32x16_bf16 v[2:17], v[86:89], v[102:105], v[2:17]
	ds_read_b128 v[82:85], v145
	ds_read_b128 v[186:189], v145 offset:32
	ds_read_b128 v[86:89], v145 offset:4608
	ds_read_b128 v[216:219], v145 offset:4640
	s_waitcnt lgkmcnt(3)
	v_mfma_f32_32x32x16_bf16 v[98:113], v[82:85], v[114:117], 0
	ds_read_b128 v[220:223], v145 offset:64
	ds_read_b128 v[224:227], v145 offset:4672
	s_waitcnt lgkmcnt(3)
	v_mfma_f32_32x32x16_bf16 v[82:97], v[86:89], v[114:117], 0
	v_mfma_f32_32x32x16_bf16 v[98:113], v[186:189], v[26:29], v[98:113]
	ds_read_b128 v[186:189], v145 offset:96
	ds_read_b128 v[240:243], v145 offset:4704
	s_waitcnt lgkmcnt(4)
	v_mfma_f32_32x32x16_bf16 v[82:97], v[216:219], v[26:29], v[82:97]
	s_waitcnt lgkmcnt(3)
	v_mfma_f32_32x32x16_bf16 v[98:113], v[220:223], v[22:25], v[98:113]
	s_waitcnt lgkmcnt(2)
	v_mfma_f32_32x32x16_bf16 v[82:97], v[224:227], v[22:25], v[82:97]
	s_waitcnt lgkmcnt(1)
	v_mfma_f32_32x32x16_bf16 v[98:113], v[186:189], v[18:21], v[98:113]
	s_waitcnt lgkmcnt(0)
	v_mfma_f32_32x32x16_bf16 v[82:97], v[240:243], v[18:21], v[82:97]
	s_nop 10
	v_max_f32_e32 v149, v98, v99
	v_max_f32_e32 v188, v90, v91
	v_max_f32_e32 v186, v106, v107
	v_max3_f32 v187, v82, v83, v84
	v_max3_f32 v188, v188, v92, v93
	v_max3_f32 v149, v149, v100, v101
	v_max3_f32 v186, v186, v108, v109
	v_max3_f32 v187, v187, v85, v86
	v_max3_f32 v188, v188, v94, v95
	v_max3_f32 v149, v149, v102, v103
	v_max3_f32 v186, v186, v110, v111
	v_max3_f32 v187, v187, v87, v88
	v_max3_f32 v188, v188, v96, v97
	v_max3_f32 v149, v149, v104, v105
	v_max3_f32 v186, v186, v112, v113
	v_max3_f32 v187, v187, v89, v188
	v_max3_f32 v149, v149, v186, v187
	v_mov_b32_e32 v186, v149
	s_nop 1
	v_permlane32_swap_b32_e32 v149, v186
	v_max_f32_e32 v149, v149, v186
	v_mul_f32_e32 v149, 0x3e38aa3b, v149
	v_max_f32_e32 v149, v151, v149
	v_sub_f32_e32 v186, v149, v151
	v_cmp_lt_f32_e32 vcc, s34, v186
	s_cbranch_vccz .LBB0_844
	v_sub_f32_e32 v150, v151, v149
	v_exp_f32_e32 v150, v150
	s_nop 0
	v_mul_f32_e32 v152, v152, v150
	v_pk_mul_f32 v[80:81], v[80:81], v[150:151] op_sel_hi:[1,0]
	v_pk_mul_f32 v[78:79], v[78:79], v[150:151] op_sel_hi:[1,0]
	v_pk_mul_f32 v[76:77], v[76:77], v[150:151] op_sel_hi:[1,0]
	v_pk_mul_f32 v[74:75], v[74:75], v[150:151] op_sel_hi:[1,0]
	v_pk_mul_f32 v[72:73], v[72:73], v[150:151] op_sel_hi:[1,0]
	v_pk_mul_f32 v[70:71], v[70:71], v[150:151] op_sel_hi:[1,0]
	v_pk_mul_f32 v[68:69], v[68:69], v[150:151] op_sel_hi:[1,0]
	v_pk_mul_f32 v[66:67], v[66:67], v[150:151] op_sel_hi:[1,0]
	v_pk_mul_f32 v[48:49], v[48:49], v[150:151] op_sel_hi:[1,0]
	v_pk_mul_f32 v[46:47], v[46:47], v[150:151] op_sel_hi:[1,0]
	v_pk_mul_f32 v[44:45], v[44:45], v[150:151] op_sel_hi:[1,0]
	v_pk_mul_f32 v[42:43], v[42:43], v[150:151] op_sel_hi:[1,0]
	v_pk_mul_f32 v[40:41], v[40:41], v[150:151] op_sel_hi:[1,0]
	v_pk_mul_f32 v[38:39], v[38:39], v[150:151] op_sel_hi:[1,0]
	v_pk_mul_f32 v[36:37], v[36:37], v[150:151] op_sel_hi:[1,0]
	v_pk_mul_f32 v[34:35], v[34:35], v[150:151] op_sel_hi:[1,0]
	v_xor_b32_e32 v150, 0x80000000, v149
	s_branch .LBB0_845

; #define LAS __attribute__((address_space(3)))
; __device__ __forceinline__ unsigned pk2(float lo, float hi) { return pg8::pkbf(lo, hi); }
; __device__ __forceinline__ float fexp2(float x) { return __builtin_amdgcn_exp2f(x); }
; #define SCHED_FENCE() __builtin_amdgcn_sched_barrier(0)
; #define PV_LOAD(dst, i) do { _Pragma("unroll") for (int d = 0; d < ND; ++d) { LAS const unsigned char* vp = vb + (16 * (i)) * VRB + d * 64; dst[2 * d] = tr_read(vp); dst[2 * d + 1] = tr_read(vp + 8 * VRB); } } while (0)
; template <int DV, bool MASK>
; __device__ __forceinline__ void attn_softmax(f32x16 (&p)[2], f32x16 (&o)[DV / 32], float& m, float& l, float cs, int hi, int dq) {
;     ...
;     float ls0 = 0.f, ls1 = 0.f, ls2 = 0.f, ls3 = 0.f;
; #pragma unroll
;     for (int kvb = 0; kvb < 2; ++kvb)
; #pragma unroll
;         for (int e = 0; e < 16; e += 4) {
;             const float e0 = fexp2(fmaf(p[kvb][e], cs, -m)), e1 = fexp2(fmaf(p[kvb][e + 1], cs, -m)), e2 = fexp2(fmaf(p[kvb][e + 2], cs, -m)), e3 = fexp2(fmaf(p[kvb][e + 3], cs, -m));
;             p[kvb][e] = e0; p[kvb][e + 1] = e1; p[kvb][e + 2] = e2; p[kvb][e + 3] = e3; ls0 += e0; ls1 += e1; ls2 += e2; ls3 += e3; }
;     l += (ls0 + ls1) + (ls2 + ls3);
; }
; template <int DV, int VRB>
; __device__ __forceinline__ void attn_pv(LAS const unsigned char* Vt, const f32x16 (&p)[2], f32x16 (&o)[DV / 32], int vtb) {
;     constexpr int ND = DV / 32;
;     LAS const unsigned char* vb = Vt + vtb;
;     bf16x8 pf[4];
; #pragma unroll
;     for (int i = 0; i < 4; ++i) { const int kvb = i >> 1, s = i & 1;
;         v4u pw; pw.x = pk2(p[kvb][8 * s + 0], p[kvb][8 * s + 1]); pw.y = pk2(p[kvb][8 * s + 2], p[kvb][8 * s + 3]); pw.z = pk2(p[kvb][8 * s + 4], p[kvb][8 * s + 5]); pw.w = pk2(p[kvb][8 * s + 6], p[kvb][8 * s + 7]);
;         pf[i] = __builtin_bit_cast(bf16x8, pw); }
;     s16x4 va[2 * ND], vbq[2 * ND];
;     ...
;     PV_LOAD(va, 0); SCHED_FENCE();
;     PV_LOAD(vbq, 1); PV_MMA(va, 0); SCHED_FENCE();
;     PV_LOAD(va, 2); PV_MMA(vbq, 1); SCHED_FENCE();
;     PV_LOAD(vbq, 3); PV_MMA(va, 2); SCHED_FENCE();
;     PV_MMA(vbq, 3); SCHED_FENCE();
; __device__ __forceinline__ void swa_unit(const bf16* Z, const float* sink  , bf16* Y, int b, int g, int blk, int cblk, LAS unsigned char* L, int tid) {
;     ...
;         if (more) SWA_STORE((t + 1) & 1);
;         __syncthreads();
.LBB0_845:
	v_add_f32_e32 v151, 0, v154
	v_add_f32_e32 v154, 0, v155
	v_add_f32_e32 v155, 0, v162
	v_add_f32_e32 v162, 0, v163
	v_add_f32_e32 v151, v164, v151
	v_add_f32_e32 v154, v166, v154
	v_add_f32_e32 v155, v167, v155
	v_add_f32_e32 v162, v168, v162
	v_add_f32_e32 v151, v169, v151
	v_add_f32_e32 v154, v181, v154
	v_add_f32_e32 v155, v182, v155
	v_add_f32_e32 v162, v183, v162
	v_add_f32_e32 v151, v196, v151
	v_add_f32_e32 v154, v197, v154
	v_add_f32_e32 v155, v198, v155
	v_add_f32_e32 v162, v199, v162
	v_add_f32_e32 v151, v200, v151
	v_add_f32_e32 v154, v201, v154
	v_add_f32_e32 v155, v202, v155
	v_add_f32_e32 v162, v203, v162
	v_add_f32_e32 v151, v204, v151
	v_add_f32_e32 v154, v205, v154
	v_add_f32_e32 v155, v206, v155
	v_add_f32_e32 v162, v207, v162
	v_add_f32_e32 v151, v208, v151
	v_add_f32_e32 v154, v209, v154
	v_add_f32_e32 v155, v210, v155
	v_add_f32_e32 v162, v211, v162
	v_add_f32_e32 v151, v212, v151
	v_add_f32_e32 v154, v213, v154
	v_add_f32_e32 v155, v214, v155
	v_add_f32_e32 v162, v215, v162
	v_add_f32_e32 v151, v151, v154
	v_add_f32_e32 v154, v155, v162
	v_add_f32_e32 v151, v151, v154
	v_fmamk_f32 v98, v98, 0x3e38aa3b, v150
	v_add_f32_e32 v151, v153, v151
	v_exp_f32_e32 v153, v98
	v_fmamk_f32 v98, v99, 0x3e38aa3b, v150
	v_fmamk_f32 v82, v82, 0x3e38aa3b, v150
	v_exp_f32_e32 v154, v98
	v_fmamk_f32 v98, v100, 0x3e38aa3b, v150
	v_exp_f32_e32 v199, v82
	v_fmamk_f32 v82, v83, 0x3e38aa3b, v150
	v_exp_f32_e32 v155, v98
	v_fmamk_f32 v98, v101, 0x3e38aa3b, v150
	v_exp_f32_e32 v200, v82
	v_fmamk_f32 v82, v84, 0x3e38aa3b, v150
	v_exp_f32_e32 v162, v98
	v_fmamk_f32 v98, v102, 0x3e38aa3b, v150
	v_exp_f32_e32 v201, v82
	v_fmamk_f32 v82, v85, 0x3e38aa3b, v150
	v_exp_f32_e32 v163, v98
	v_fmamk_f32 v98, v103, 0x3e38aa3b, v150
	v_exp_f32_e32 v202, v82
	v_fmamk_f32 v82, v86, 0x3e38aa3b, v150
	v_exp_f32_e32 v164, v98
	v_fmamk_f32 v98, v104, 0x3e38aa3b, v150
	v_exp_f32_e32 v203, v82
	v_fmamk_f32 v82, v87, 0x3e38aa3b, v150
	v_exp_f32_e32 v166, v98
	v_fmamk_f32 v98, v105, 0x3e38aa3b, v150
	v_exp_f32_e32 v204, v82
	v_fmamk_f32 v82, v88, 0x3e38aa3b, v150
	v_exp_f32_e32 v167, v98
	v_fmamk_f32 v98, v106, 0x3e38aa3b, v150
	v_exp_f32_e32 v205, v82
	v_fmamk_f32 v82, v89, 0x3e38aa3b, v150
	v_exp_f32_e32 v168, v98
	v_fmamk_f32 v98, v107, 0x3e38aa3b, v150
	v_exp_f32_e32 v206, v82
	v_fmamk_f32 v82, v90, 0x3e38aa3b, v150
	v_exp_f32_e32 v169, v98
	v_fmamk_f32 v98, v108, 0x3e38aa3b, v150
	v_exp_f32_e32 v207, v82
	v_fmamk_f32 v82, v91, 0x3e38aa3b, v150
	v_exp_f32_e32 v181, v98
	v_fmamk_f32 v98, v109, 0x3e38aa3b, v150
	v_exp_f32_e32 v208, v82
	v_fmamk_f32 v82, v92, 0x3e38aa3b, v150
	v_exp_f32_e32 v182, v98
	v_fmamk_f32 v98, v110, 0x3e38aa3b, v150
	v_exp_f32_e32 v209, v82
	v_fmamk_f32 v82, v93, 0x3e38aa3b, v150
	v_exp_f32_e32 v183, v98
	v_fmamk_f32 v98, v111, 0x3e38aa3b, v150
	v_exp_f32_e32 v210, v82
	v_fmamk_f32 v82, v94, 0x3e38aa3b, v150
	v_exp_f32_e32 v196, v98
	v_fmamk_f32 v98, v112, 0x3e38aa3b, v150
	v_exp_f32_e32 v211, v82
	v_fmamk_f32 v82, v95, 0x3e38aa3b, v150
	v_exp_f32_e32 v197, v98
	v_fmamk_f32 v98, v113, 0x3e38aa3b, v150
	v_exp_f32_e32 v212, v82
	v_fmamk_f32 v82, v96, 0x3e38aa3b, v150
	v_exp_f32_e32 v198, v98
	v_exp_f32_e32 v213, v82
	v_fmamk_f32 v82, v97, 0x3e38aa3b, v150
	ds_read_b64_tr_b16 v[94:95], v179 offset:9216
	ds_read_b64_tr_b16 v[96:97], v179 offset:10752
	ds_read_b64_tr_b16 v[100:101], v179 offset:10816
	ds_read_b64_tr_b16 v[98:99], v179 offset:9280
	v_exp_f32_e32 v214, v82
	v_cvt_pk_bf16_f32 v82, v153, v154
	v_cvt_pk_bf16_f32 v83, v155, v162
	v_cvt_pk_bf16_f32 v84, v163, v164
	v_cvt_pk_bf16_f32 v85, v166, v167
	v_cvt_pk_bf16_f32 v86, v168, v169
	v_cvt_pk_bf16_f32 v87, v181, v182
	v_cvt_pk_bf16_f32 v88, v183, v196
	v_cvt_pk_bf16_f32 v89, v197, v198
	v_cvt_pk_bf16_f32 v90, v199, v200
	v_cvt_pk_bf16_f32 v91, v201, v202
	v_cvt_pk_bf16_f32 v92, v203, v204
	v_cvt_pk_bf16_f32 v93, v205, v206
	v_cvt_pk_bf16_f32 v102, v207, v208
	v_cvt_pk_bf16_f32 v103, v209, v210
	v_cvt_pk_bf16_f32 v104, v211, v212
	v_cvt_pk_bf16_f32 v105, v213, v214
	s_waitcnt lgkmcnt(2)
	v_mfma_f32_32x32x16_bf16 v[66:81], v[94:97], v[82:85], v[66:81]
	ds_read_b64_tr_b16 v[94:95], v179 offset:12288
	ds_read_b64_tr_b16 v[96:97], v179 offset:13824
	ds_read_b64_tr_b16 v[108:109], v179 offset:13888
	ds_read_b64_tr_b16 v[106:107], v179 offset:12352
	s_waitcnt lgkmcnt(4)
	v_mfma_f32_32x32x16_bf16 v[34:49], v[98:101], v[82:85], v[34:49]
	s_waitcnt lgkmcnt(2)
	v_mfma_f32_32x32x16_bf16 v[66:81], v[94:97], v[86:89], v[66:81]
	ds_read_b64_tr_b16 v[82:83], v179 offset:15360
	ds_read_b64_tr_b16 v[84:85], v179 offset:16896
	ds_read_b64_tr_b16 v[96:97], v179 offset:16960
	ds_read_b64_tr_b16 v[94:95], v179 offset:15424
	s_waitcnt lgkmcnt(4)
	v_mfma_f32_32x32x16_bf16 v[34:49], v[106:109], v[86:89], v[34:49]
	s_waitcnt lgkmcnt(2)
	v_mfma_f32_32x32x16_bf16 v[66:81], v[82:85], v[90:93], v[66:81]
	ds_read_b64_tr_b16 v[82:83], v179 offset:18432
	ds_read_b64_tr_b16 v[84:85], v179 offset:19968
	ds_read_b64_tr_b16 v[88:89], v179 offset:20032
	ds_read_b64_tr_b16 v[86:87], v179 offset:18496
	s_waitcnt lgkmcnt(4)
	v_mfma_f32_32x32x16_bf16 v[34:49], v[94:97], v[90:93], v[34:49]
	s_waitcnt lgkmcnt(2)
	v_mfma_f32_32x32x16_bf16 v[66:81], v[82:85], v[102:105], v[66:81]
	s_waitcnt lgkmcnt(0)
	v_mfma_f32_32x32x16_bf16 v[34:49], v[86:89], v[102:105], v[34:49]
	s_waitcnt vmcnt(1)
	ds_write_b128 v174, v[134:137] offset:21504
	s_waitcnt vmcnt(0)
	ds_write_b128 v165, v[138:141] offset:30720
	s_waitcnt lgkmcnt(0)
	s_barrier
; template <int DQK, int KSB>
; __device__ __forceinline__ void attn_scores(LAS const unsigned char* Kt, const bf16x8 (&qf)[DQK / 16], f32x16 (&p)[2], int r32, int hi) {
;     constexpr int NK = DQK / 16;
;     LAS const unsigned char* kp = Kt + r32 * KSB + hi * 16;
;     f32x16 p0, p1;
; #pragma unroll
;     for (int e = 0; e < 16; ++e) { p0[e] = 0.f; p1[e] = 0.f; }
;     bf16x8 kr[3][2];
;     ...
;     QK_LOAD(0); QK_LOAD(1); SCHED_FENCE();
; #pragma unroll
;     for (int ks = 0; ks < NK; ++ks) {
;         if (ks + 2 < NK) QK_LOAD(ks + 2);
;         p0 = MFMA32(kr[ks % 3][0], qf[ks], p0); p1 = MFMA32(kr[ks % 3][1], qf[ks], p1); SCHED_FENCE();
;     }
;     ...
;     p[0] = p0; p[1] = p1;
; }
; template <int DV, bool MASK>
; __device__ __forceinline__ void attn_softmax(f32x16 (&p)[2], f32x16 (&o)[DV / 32], float& m, float& l, float cs, int hi, int dq) {
;     if (MASK) { if (__builtin_amdgcn_readfirstlane(dq) != NO_MASK) {
; #pragma unroll
;         for (int kvb = 0; kvb < 2; ++kvb)
; #pragma unroll
;             for (int e = 0; e < 16; ++e) { const int rel = dq + 32 * kvb + (e & 3) + 8 * (e >> 2) + 4 * hi; if (rel > 128 || rel < -128) p[kvb][e] = -INFINITY; } } }
;     float mx;
;     {
;         float a0 = fmaxf(fmaxf(p[0][0], p[0][1]), p[0][2]), a1 = fmaxf(fmaxf(p[0][8], p[0][9]), p[0][10]), a2 = fmaxf(fmaxf(p[1][0], p[1][1]), p[1][2]), a3 = fmaxf(fmaxf(p[1][8], p[1][9]), p[1][10]);
;         a0 = fmaxf(fmaxf(a0, p[0][3]), p[0][4]); a1 = fmaxf(fmaxf(a1, p[0][11]), p[0][12]); a2 = fmaxf(fmaxf(a2, p[1][3]), p[1][4]); a3 = fmaxf(fmaxf(a3, p[1][11]), p[1][12]);
;         a0 = fmaxf(fmaxf(a0, p[0][5]), p[0][6]); a1 = fmaxf(fmaxf(a1, p[0][13]), p[0][14]); a2 = fmaxf(fmaxf(a2, p[1][5]), p[1][6]); a3 = fmaxf(fmaxf(a3, p[1][13]), p[1][14]);
;         a0 = fmaxf(a0, p[0][7]); a1 = fmaxf(a1, p[0][15]); a2 = fmaxf(a2, p[1][7]); a3 = fmaxf(a3, p[1][15]);
;         mx = fmaxf(fmaxf(a0, a1), fmaxf(a2, a3));
;         const auto rr = __builtin_amdgcn_permlane32_swap(__float_as_uint(mx), __float_as_uint(mx), false, false);
;         mx = fmaxf(__uint_as_float(rr[0]), __uint_as_float(rr[1])); }
;     const float mn = fmaxf(m, mx * cs);
;     if (__any(mn - m > ATT_THR)) {
;         const float alpha = fexp2(m - mn); m = mn; l *= alpha;
; #pragma unroll
;         for (int d = 0; d < DV / 32; ++d)
; #pragma unroll
;             for (int e = 0; e < 16; ++e) o[d][e] *= alpha;
;     }
	ds_read_b128 v[82:85], v145 offset:21504
	ds_read_b128 v[134:137], v145 offset:21536
	ds_read_b128 v[86:89], v145 offset:26112
	ds_read_b128 v[138:141], v145 offset:26144
	s_waitcnt lgkmcnt(3)
	v_mfma_f32_32x32x16_bf16 v[98:113], v[82:85], v[130:133], 0
	ds_read_b128 v[186:189], v145 offset:21568
	ds_read_b128 v[216:219], v145 offset:26176
	s_waitcnt lgkmcnt(3)
	v_mfma_f32_32x32x16_bf16 v[82:97], v[86:89], v[130:133], 0
	v_mfma_f32_32x32x16_bf16 v[98:113], v[134:137], v[126:129], v[98:113]
	ds_read_b128 v[130:133], v145 offset:21600
	ds_read_b128 v[134:137], v145 offset:26208
	s_waitcnt lgkmcnt(4)
	v_mfma_f32_32x32x16_bf16 v[82:97], v[138:141], v[126:129], v[82:97]
	s_waitcnt lgkmcnt(3)
	v_mfma_f32_32x32x16_bf16 v[98:113], v[186:189], v[122:125], v[98:113]
	s_waitcnt lgkmcnt(2)
	v_mfma_f32_32x32x16_bf16 v[82:97], v[216:219], v[122:125], v[82:97]
	s_waitcnt lgkmcnt(1)
	v_mfma_f32_32x32x16_bf16 v[98:113], v[130:133], v[118:121], v[98:113]
	s_waitcnt lgkmcnt(0)
	v_mfma_f32_32x32x16_bf16 v[82:97], v[134:137], v[118:121], v[82:97]
	s_nop 10
	v_max_f32_e32 v118, v98, v99
	v_max_f32_e32 v121, v90, v91
	v_max_f32_e32 v119, v106, v107
	v_max3_f32 v120, v82, v83, v84
	v_max3_f32 v121, v121, v92, v93
	v_max3_f32 v118, v118, v100, v101
	v_max3_f32 v119, v119, v108, v109
	v_max3_f32 v120, v120, v85, v86
	v_max3_f32 v121, v121, v94, v95
	v_max3_f32 v118, v118, v102, v103
	v_max3_f32 v119, v119, v110, v111
	v_max3_f32 v120, v120, v87, v88
	v_max3_f32 v121, v121, v96, v97
	v_max3_f32 v118, v118, v104, v105
	v_max3_f32 v119, v119, v112, v113
	v_max3_f32 v120, v120, v89, v121
	v_max3_f32 v118, v118, v119, v120
	v_mov_b32_e32 v119, v118
	s_nop 1
	v_permlane32_swap_b32_e32 v118, v119
	v_max_f32_e32 v118, v118, v119
	v_mul_f32_e32 v118, 0x3e38aa3b, v118
	v_max_f32_e32 v118, v148, v118
	v_sub_f32_e32 v119, v118, v148
	v_cmp_lt_f32_e32 vcc, s34, v119
	s_cbranch_vccz .LBB0_847
	v_sub_f32_e32 v119, v148, v118
	v_exp_f32_e32 v120, v119
	v_xor_b32_e32 v147, 0x80000000, v118
	v_mul_f32_e32 v151, v151, v120
	v_pk_mul_f32 v[64:65], v[64:65], v[120:121] op_sel_hi:[1,0]
	v_pk_mul_f32 v[62:63], v[62:63], v[120:121] op_sel_hi:[1,0]
	v_pk_mul_f32 v[60:61], v[60:61], v[120:121] op_sel_hi:[1,0]
	v_pk_mul_f32 v[58:59], v[58:59], v[120:121] op_sel_hi:[1,0]
	v_pk_mul_f32 v[56:57], v[56:57], v[120:121] op_sel_hi:[1,0]
	v_pk_mul_f32 v[54:55], v[54:55], v[120:121] op_sel_hi:[1,0]
	v_pk_mul_f32 v[52:53], v[52:53], v[120:121] op_sel_hi:[1,0]
	v_pk_mul_f32 v[50:51], v[50:51], v[120:121] op_sel_hi:[1,0]
	v_pk_mul_f32 v[16:17], v[16:17], v[120:121] op_sel_hi:[1,0]
	v_pk_mul_f32 v[14:15], v[14:15], v[120:121] op_sel_hi:[1,0]
	v_pk_mul_f32 v[12:13], v[12:13], v[120:121] op_sel_hi:[1,0]
	v_pk_mul_f32 v[10:11], v[10:11], v[120:121] op_sel_hi:[1,0]
	v_pk_mul_f32 v[8:9], v[8:9], v[120:121] op_sel_hi:[1,0]
	v_pk_mul_f32 v[6:7], v[6:7], v[120:121] op_sel_hi:[1,0]
	v_pk_mul_f32 v[4:5], v[4:5], v[120:121] op_sel_hi:[1,0]
	v_pk_mul_f32 v[2:3], v[2:3], v[120:121] op_sel_hi:[1,0]
.LBB0_847:
	v_add_f32_e32 v118, 0, v153
	v_add_f32_e32 v119, 0, v154
	v_add_f32_e32 v120, 0, v155
	v_add_f32_e32 v121, 0, v162
	v_add_f32_e32 v118, v163, v118
	v_add_f32_e32 v119, v164, v119
	v_add_f32_e32 v120, v166, v120
	v_add_f32_e32 v121, v167, v121
	v_add_f32_e32 v118, v168, v118
	v_add_f32_e32 v119, v169, v119
	v_add_f32_e32 v120, v181, v120
	v_add_f32_e32 v121, v182, v121
	v_add_f32_e32 v118, v183, v118
	v_add_f32_e32 v119, v196, v119
	v_add_f32_e32 v120, v197, v120
	v_add_f32_e32 v121, v198, v121
	v_add_f32_e32 v118, v199, v118
	v_add_f32_e32 v119, v200, v119
	v_add_f32_e32 v120, v201, v120
	v_add_f32_e32 v121, v202, v121
	v_add_f32_e32 v118, v203, v118
	v_add_f32_e32 v119, v204, v119
	v_add_f32_e32 v120, v205, v120
	v_add_f32_e32 v121, v206, v121
	v_add_f32_e32 v118, v207, v118
	v_add_f32_e32 v119, v208, v119
	v_add_f32_e32 v120, v209, v120
	v_add_f32_e32 v121, v210, v121
	v_add_f32_e32 v118, v211, v118
	v_add_f32_e32 v119, v212, v119
	v_add_f32_e32 v120, v213, v120
	v_add_f32_e32 v121, v214, v121
	v_add_f32_e32 v118, v118, v119
	v_add_f32_e32 v119, v120, v121
	v_fmamk_f32 v98, v98, 0x3e38aa3b, v147
	v_add_f32_e32 v118, v118, v119
	v_exp_f32_e32 v119, v98
	v_fmamk_f32 v98, v99, 0x3e38aa3b, v147
	v_exp_f32_e32 v120, v98
	v_fmamk_f32 v98, v100, 0x3e38aa3b, v147
	v_fmamk_f32 v82, v82, 0x3e38aa3b, v147
	v_exp_f32_e32 v121, v98
	v_fmamk_f32 v98, v101, 0x3e38aa3b, v147
	v_exp_f32_e32 v135, v82
	v_fmamk_f32 v82, v83, 0x3e38aa3b, v147
	v_exp_f32_e32 v122, v98
	v_fmamk_f32 v98, v102, 0x3e38aa3b, v147
	v_exp_f32_e32 v136, v82
	v_fmamk_f32 v82, v84, 0x3e38aa3b, v147
	v_exp_f32_e32 v123, v98
	v_fmamk_f32 v98, v103, 0x3e38aa3b, v147
	v_exp_f32_e32 v137, v82
	v_fmamk_f32 v82, v85, 0x3e38aa3b, v147
	v_exp_f32_e32 v124, v98
	v_fmamk_f32 v98, v104, 0x3e38aa3b, v147
	v_exp_f32_e32 v138, v82
	v_fmamk_f32 v82, v86, 0x3e38aa3b, v147
	v_exp_f32_e32 v125, v98
	v_fmamk_f32 v98, v105, 0x3e38aa3b, v147
	v_exp_f32_e32 v139, v82
	v_fmamk_f32 v82, v87, 0x3e38aa3b, v147
	v_exp_f32_e32 v126, v98
	v_fmamk_f32 v98, v106, 0x3e38aa3b, v147
	v_exp_f32_e32 v140, v82
	v_fmamk_f32 v82, v88, 0x3e38aa3b, v147
	v_exp_f32_e32 v127, v98
	v_fmamk_f32 v98, v107, 0x3e38aa3b, v147
	v_exp_f32_e32 v141, v82
	v_fmamk_f32 v82, v89, 0x3e38aa3b, v147
	v_exp_f32_e32 v128, v98
	v_fmamk_f32 v98, v108, 0x3e38aa3b, v147
	v_exp_f32_e32 v148, v82
	v_fmamk_f32 v82, v90, 0x3e38aa3b, v147
	v_add_f32_e32 v118, v152, v118
	v_exp_f32_e32 v129, v98
	v_fmamk_f32 v98, v109, 0x3e38aa3b, v147
	v_exp_f32_e32 v152, v82
	v_fmamk_f32 v82, v91, 0x3e38aa3b, v147
	v_exp_f32_e32 v130, v98
	v_fmamk_f32 v98, v110, 0x3e38aa3b, v147
	v_exp_f32_e32 v153, v82
	v_fmamk_f32 v82, v92, 0x3e38aa3b, v147
	v_exp_f32_e32 v131, v98
	v_fmamk_f32 v98, v111, 0x3e38aa3b, v147
	v_exp_f32_e32 v154, v82
	v_fmamk_f32 v82, v93, 0x3e38aa3b, v147
	v_exp_f32_e32 v132, v98
	v_fmamk_f32 v98, v112, 0x3e38aa3b, v147
	v_exp_f32_e32 v155, v82
	v_fmamk_f32 v82, v94, 0x3e38aa3b, v147
	v_exp_f32_e32 v133, v98
	v_fmamk_f32 v98, v113, 0x3e38aa3b, v147
	v_exp_f32_e32 v162, v82
	v_fmamk_f32 v82, v95, 0x3e38aa3b, v147
	v_exp_f32_e32 v134, v98
	v_exp_f32_e32 v163, v82
	v_fmamk_f32 v82, v96, 0x3e38aa3b, v147
	v_fmac_f32_e32 v147, 0x3e38aa3b, v97
	ds_read_b64_tr_b16 v[94:95], v179 offset:30720
	ds_read_b64_tr_b16 v[96:97], v179 offset:32256
	ds_read_b64_tr_b16 v[100:101], v179 offset:32320
	ds_read_b64_tr_b16 v[98:99], v179 offset:30784
	v_exp_f32_e32 v164, v82
	v_exp_f32_e32 v166, v147
	v_cvt_pk_bf16_f32 v82, v119, v120
	v_cvt_pk_bf16_f32 v83, v121, v122
	v_cvt_pk_bf16_f32 v84, v123, v124
	v_cvt_pk_bf16_f32 v85, v125, v126
	v_cvt_pk_bf16_f32 v86, v127, v128
	v_cvt_pk_bf16_f32 v87, v129, v130
	v_cvt_pk_bf16_f32 v88, v131, v132
	v_cvt_pk_bf16_f32 v89, v133, v134
	v_cvt_pk_bf16_f32 v90, v135, v136
	v_cvt_pk_bf16_f32 v91, v137, v138
	v_cvt_pk_bf16_f32 v92, v139, v140
	v_cvt_pk_bf16_f32 v93, v141, v148
	v_cvt_pk_bf16_f32 v102, v152, v153
	v_cvt_pk_bf16_f32 v103, v154, v155
	v_cvt_pk_bf16_f32 v104, v162, v163
	v_cvt_pk_bf16_f32 v105, v164, v166
	s_waitcnt lgkmcnt(2)
; #define LAS __attribute__((address_space(3)))
; template <int DQK, int KSB>
; __device__ __forceinline__ void attn_scores(LAS const unsigned char* Kt, const bf16x8 (&qf)[DQK / 16], f32x16 (&p)[2], int r32, int hi) {
;     constexpr int NK = DQK / 16;
;     LAS const unsigned char* kp = Kt + r32 * KSB + hi * 16;
;     f32x16 p0, p1;
; #pragma unroll
;     for (int e = 0; e < 16; ++e) { p0[e] = 0.f; p1[e] = 0.f; }
;     bf16x8 kr[3][2];
;     ...
;     QK_LOAD(0); QK_LOAD(1); SCHED_FENCE();
; #pragma unroll
;     for (int ks = 0; ks < NK; ++ks) {
;         if (ks + 2 < NK) QK_LOAD(ks + 2);
;         p0 = MFMA32(kr[ks % 3][0], qf[ks], p0); p1 = MFMA32(kr[ks % 3][1], qf[ks], p1); SCHED_FENCE();
;     }
;     ...
;     p[0] = p0; p[1] = p1;
; }
; template <int DV, bool MASK>
; __device__ __forceinline__ void attn_softmax(f32x16 (&p)[2], f32x16 (&o)[DV / 32], float& m, float& l, float cs, int hi, int dq) {
;     if (MASK) { if (__builtin_amdgcn_readfirstlane(dq) != NO_MASK) {
; #pragma unroll
;         for (int kvb = 0; kvb < 2; ++kvb)
; #pragma unroll
;             for (int e = 0; e < 16; ++e) { const int rel = dq + 32 * kvb + (e & 3) + 8 * (e >> 2) + 4 * hi; if (rel > 128 || rel < -128) p[kvb][e] = -INFINITY; } } }
;     float mx;
;     {
;         float a0 = fmaxf(fmaxf(p[0][0], p[0][1]), p[0][2]), a1 = fmaxf(fmaxf(p[0][8], p[0][9]), p[0][10]), a2 = fmaxf(fmaxf(p[1][0], p[1][1]), p[1][2]), a3 = fmaxf(fmaxf(p[1][8], p[1][9]), p[1][10]);
;         a0 = fmaxf(fmaxf(a0, p[0][3]), p[0][4]); a1 = fmaxf(fmaxf(a1, p[0][11]), p[0][12]); a2 = fmaxf(fmaxf(a2, p[1][3]), p[1][4]); a3 = fmaxf(fmaxf(a3, p[1][11]), p[1][12]);
;         a0 = fmaxf(fmaxf(a0, p[0][5]), p[0][6]); a1 = fmaxf(fmaxf(a1, p[0][13]), p[0][14]); a2 = fmaxf(fmaxf(a2, p[1][5]), p[1][6]); a3 = fmaxf(fmaxf(a3, p[1][13]), p[1][14]);
;         a0 = fmaxf(a0, p[0][7]); a1 = fmaxf(a1, p[0][15]); a2 = fmaxf(a2, p[1][7]); a3 = fmaxf(a3, p[1][15]);
;         mx = fmaxf(fmaxf(a0, a1), fmaxf(a2, a3));
; template <int DV, int VRB>
; __device__ __forceinline__ void attn_pv(LAS const unsigned char* Vt, const f32x16 (&p)[2], f32x16 (&o)[DV / 32], int vtb) {
;     ...
;     PV_LOAD(va, 0); SCHED_FENCE();
;     PV_LOAD(vbq, 1); PV_MMA(va, 0); SCHED_FENCE();
;     PV_LOAD(va, 2); PV_MMA(vbq, 1); SCHED_FENCE();
;     PV_LOAD(vbq, 3); PV_MMA(va, 2); SCHED_FENCE();
;     PV_MMA(vbq, 3); SCHED_FENCE();
	v_mfma_f32_32x32x16_bf16 v[50:65], v[94:97], v[82:85], v[50:65]
	ds_read_b64_tr_b16 v[94:95], v179 offset:33792
	ds_read_b64_tr_b16 v[96:97], v179 offset:35328
	ds_read_b64_tr_b16 v[108:109], v179 offset:35392
	ds_read_b64_tr_b16 v[106:107], v179 offset:33856
	s_waitcnt lgkmcnt(4)
	v_mfma_f32_32x32x16_bf16 v[2:17], v[98:101], v[82:85], v[2:17]
	s_waitcnt lgkmcnt(2)
	v_mfma_f32_32x32x16_bf16 v[50:65], v[94:97], v[86:89], v[50:65]
	ds_read_b64_tr_b16 v[82:83], v179 offset:36864
	ds_read_b64_tr_b16 v[84:85], v179 offset:38400
	ds_read_b64_tr_b16 v[96:97], v179 offset:38464
	ds_read_b64_tr_b16 v[94:95], v179 offset:36928
	s_waitcnt lgkmcnt(4)
	v_mfma_f32_32x32x16_bf16 v[2:17], v[106:109], v[86:89], v[2:17]
	s_waitcnt lgkmcnt(2)
	v_mfma_f32_32x32x16_bf16 v[50:65], v[82:85], v[90:93], v[50:65]
	ds_read_b64_tr_b16 v[82:83], v179 offset:39936
	ds_read_b64_tr_b16 v[84:85], v179 offset:41472
	ds_read_b64_tr_b16 v[88:89], v179 offset:41536
	ds_read_b64_tr_b16 v[86:87], v179 offset:40000
	s_waitcnt lgkmcnt(4)
	v_mfma_f32_32x32x16_bf16 v[2:17], v[94:97], v[90:93], v[2:17]
	s_waitcnt lgkmcnt(2)
	v_mfma_f32_32x32x16_bf16 v[50:65], v[82:85], v[102:105], v[50:65]
	s_waitcnt lgkmcnt(0)
	v_mfma_f32_32x32x16_bf16 v[2:17], v[86:89], v[102:105], v[2:17]
	ds_read_b128 v[82:85], v145 offset:21504
	ds_read_b128 v[186:189], v145 offset:21536
	ds_read_b128 v[86:89], v145 offset:26112
	ds_read_b128 v[196:199], v145 offset:26144
	s_waitcnt lgkmcnt(3)
	v_mfma_f32_32x32x16_bf16 v[98:113], v[82:85], v[114:117], 0
	ds_read_b128 v[200:203], v145 offset:21568
	ds_read_b128 v[204:207], v145 offset:26176
	s_waitcnt lgkmcnt(3)
	v_mfma_f32_32x32x16_bf16 v[82:97], v[86:89], v[114:117], 0
	v_mfma_f32_32x32x16_bf16 v[98:113], v[186:189], v[26:29], v[98:113]
	ds_read_b128 v[114:117], v145 offset:21600
	ds_read_b128 v[186:189], v145 offset:26208
	s_waitcnt lgkmcnt(4)
	v_mfma_f32_32x32x16_bf16 v[82:97], v[196:199], v[26:29], v[82:97]
	s_waitcnt lgkmcnt(3)
	v_mfma_f32_32x32x16_bf16 v[98:113], v[200:203], v[22:25], v[98:113]
	s_waitcnt lgkmcnt(2)
	v_mfma_f32_32x32x16_bf16 v[82:97], v[204:207], v[22:25], v[82:97]
	s_waitcnt lgkmcnt(1)
	v_mfma_f32_32x32x16_bf16 v[98:113], v[114:117], v[18:21], v[98:113]
	s_waitcnt lgkmcnt(0)
	v_mfma_f32_32x32x16_bf16 v[82:97], v[186:189], v[18:21], v[82:97]
	s_nop 10
	v_max_f32_e32 v18, v98, v99
	v_max_f32_e32 v21, v90, v91
	v_max_f32_e32 v19, v106, v107
	v_max3_f32 v20, v82, v83, v84
	v_max3_f32 v21, v21, v92, v93
	v_max3_f32 v18, v18, v100, v101
	v_max3_f32 v19, v19, v108, v109
	v_max3_f32 v20, v20, v85, v86
	v_max3_f32 v21, v21, v94, v95
	v_max3_f32 v18, v18, v102, v103
	v_max3_f32 v19, v19, v110, v111
	v_max3_f32 v20, v20, v87, v88
	v_max3_f32 v21, v21, v96, v97
	v_max3_f32 v18, v18, v104, v105
	v_max3_f32 v19, v19, v112, v113
	v_max3_f32 v20, v20, v89, v21
	v_max3_f32 v18, v18, v19, v20
	v_mov_b32_e32 v19, v18
	s_nop 1
	v_permlane32_swap_b32_e32 v18, v19
	v_max_f32_e32 v18, v18, v19
	v_mul_f32_e32 v18, 0x3e38aa3b, v18
	v_max_f32_e32 v18, v149, v18
	v_sub_f32_e32 v19, v18, v149
	v_cmp_lt_f32_e32 vcc, s34, v19
	s_cbranch_vccz .LBB0_849
	v_sub_f32_e32 v19, v149, v18
	v_exp_f32_e32 v20, v19
	v_xor_b32_e32 v150, 0x80000000, v18
	v_mul_f32_e32 v118, v118, v20
	v_pk_mul_f32 v[80:81], v[80:81], v[20:21] op_sel_hi:[1,0]
	v_pk_mul_f32 v[78:79], v[78:79], v[20:21] op_sel_hi:[1,0]
	v_pk_mul_f32 v[76:77], v[76:77], v[20:21] op_sel_hi:[1,0]
	v_pk_mul_f32 v[74:75], v[74:75], v[20:21] op_sel_hi:[1,0]
	v_pk_mul_f32 v[72:73], v[72:73], v[20:21] op_sel_hi:[1,0]
	v_pk_mul_f32 v[70:71], v[70:71], v[20:21] op_sel_hi:[1,0]
	v_pk_mul_f32 v[68:69], v[68:69], v[20:21] op_sel_hi:[1,0]
	v_pk_mul_f32 v[66:67], v[66:67], v[20:21] op_sel_hi:[1,0]
	v_pk_mul_f32 v[48:49], v[48:49], v[20:21] op_sel_hi:[1,0]
	v_pk_mul_f32 v[46:47], v[46:47], v[20:21] op_sel_hi:[1,0]
	v_pk_mul_f32 v[44:45], v[44:45], v[20:21] op_sel_hi:[1,0]
	v_pk_mul_f32 v[42:43], v[42:43], v[20:21] op_sel_hi:[1,0]
	v_pk_mul_f32 v[40:41], v[40:41], v[20:21] op_sel_hi:[1,0]
	v_pk_mul_f32 v[38:39], v[38:39], v[20:21] op_sel_hi:[1,0]
	v_pk_mul_f32 v[36:37], v[36:37], v[20:21] op_sel_hi:[1,0]
	v_pk_mul_f32 v[34:35], v[34:35], v[20:21] op_sel_hi:[1,0]

; __device__ __forceinline__ float fexp2(float x) { return __builtin_amdgcn_exp2f(x); }
; template <int DV, bool MASK>
; __device__ __forceinline__ void attn_softmax(f32x16 (&p)[2], f32x16 (&o)[DV / 32], float& m, float& l, float cs, int hi, int dq) {
;     if (MASK) { if (__builtin_amdgcn_readfirstlane(dq) != NO_MASK) {
; #pragma unroll
;         for (int kvb = 0; kvb < 2; ++kvb)
; #pragma unroll
;             for (int e = 0; e < 16; ++e) { const int rel = dq + 32 * kvb + (e & 3) + 8 * (e >> 2) + 4 * hi; if (rel > 128 || rel < -128) p[kvb][e] = -INFINITY; } } }
;     float mx;
;     {
;         float a0 = fmaxf(fmaxf(p[0][0], p[0][1]), p[0][2]), a1 = fmaxf(fmaxf(p[0][8], p[0][9]), p[0][10]), a2 = fmaxf(fmaxf(p[1][0], p[1][1]), p[1][2]), a3 = fmaxf(fmaxf(p[1][8], p[1][9]), p[1][10]);
;         a0 = fmaxf(fmaxf(a0, p[0][3]), p[0][4]); a1 = fmaxf(fmaxf(a1, p[0][11]), p[0][12]); a2 = fmaxf(fmaxf(a2, p[1][3]), p[1][4]); a3 = fmaxf(fmaxf(a3, p[1][11]), p[1][12]);
;         a0 = fmaxf(fmaxf(a0, p[0][5]), p[0][6]); a1 = fmaxf(fmaxf(a1, p[0][13]), p[0][14]); a2 = fmaxf(fmaxf(a2, p[1][5]), p[1][6]); a3 = fmaxf(fmaxf(a3, p[1][13]), p[1][14]);
;         a0 = fmaxf(a0, p[0][7]); a1 = fmaxf(a1, p[0][15]); a2 = fmaxf(a2, p[1][7]); a3 = fmaxf(a3, p[1][15]);
;         mx = fmaxf(fmaxf(a0, a1), fmaxf(a2, a3));
;         const auto rr = __builtin_amdgcn_permlane32_swap(__float_as_uint(mx), __float_as_uint(mx), false, false);
;         mx = fmaxf(__uint_as_float(rr[0]), __uint_as_float(rr[1])); }
;     const float mn = fmaxf(m, mx * cs);
;     if (__any(mn - m > ATT_THR)) {
;         const float alpha = fexp2(m - mn); m = mn; l *= alpha;
; #pragma unroll
;         for (int d = 0; d < DV / 32; ++d)
; #pragma unroll
;             for (int e = 0; e < 16; ++e) o[d][e] *= alpha;
;     }
.LBB0_859:
	s_nop 6
	v_max_f32_e32 v35, v113, v113
	v_max_f32_e32 v37, v112, v112
	v_max_f32_e32 v39, v105, v105
	v_max_f32_e32 v40, v104, v104
	v_max_f32_e32 v35, v37, v35
	v_max_f32_e32 v37, v121, v121
	v_max_f32_e32 v38, v120, v120
	v_max_f32_e32 v39, v40, v39
	v_max_f32_e32 v37, v38, v37
	v_max3_f32 v38, v96, v97, v98
	v_max3_f32 v39, v39, v106, v107
	v_max3_f32 v35, v35, v114, v115
	v_max3_f32 v37, v37, v122, v123
	v_max3_f32 v38, v38, v99, v100
	v_max3_f32 v39, v39, v108, v109
	v_max3_f32 v35, v35, v116, v117
	v_max3_f32 v37, v37, v124, v125
	v_max3_f32 v38, v38, v101, v102
	v_max3_f32 v39, v39, v110, v111
	v_max3_f32 v35, v35, v118, v119
	v_max3_f32 v37, v37, v126, v127
	v_max3_f32 v38, v38, v103, v39
	v_max3_f32 v35, v35, v37, v38
	v_mov_b32_e32 v37, v35
	s_nop 1
	v_permlane32_swap_b32_e32 v35, v37
	v_max_f32_e32 v35, v35, v37
	v_mul_f32_e32 v35, 0x3e38aa3b, v35
	v_max_f32_e32 v35, v36, v35
	v_sub_f32_e32 v37, v35, v36
	v_cmp_lt_f32_e32 vcc, s34, v37
	s_cbranch_vccz .LBB0_861
	v_sub_f32_e32 v36, v36, v35
	v_exp_f32_e32 v36, v36
	s_nop 0
	v_mul_f32_e32 v34, v34, v36
	v_pk_mul_f32 v[94:95], v[94:95], v[36:37] op_sel_hi:[1,0]
	v_pk_mul_f32 v[92:93], v[92:93], v[36:37] op_sel_hi:[1,0]
	v_pk_mul_f32 v[90:91], v[90:91], v[36:37] op_sel_hi:[1,0]
	v_pk_mul_f32 v[88:89], v[88:89], v[36:37] op_sel_hi:[1,0]
	v_pk_mul_f32 v[86:87], v[86:87], v[36:37] op_sel_hi:[1,0]
	v_pk_mul_f32 v[84:85], v[84:85], v[36:37] op_sel_hi:[1,0]
	v_pk_mul_f32 v[82:83], v[82:83], v[36:37] op_sel_hi:[1,0]
	v_pk_mul_f32 v[80:81], v[80:81], v[36:37] op_sel_hi:[1,0]
	v_pk_mul_f32 v[78:79], v[78:79], v[36:37] op_sel_hi:[1,0]
	v_pk_mul_f32 v[76:77], v[76:77], v[36:37] op_sel_hi:[1,0]
	v_pk_mul_f32 v[74:75], v[74:75], v[36:37] op_sel_hi:[1,0]
	v_pk_mul_f32 v[72:73], v[72:73], v[36:37] op_sel_hi:[1,0]
	v_pk_mul_f32 v[70:71], v[70:71], v[36:37] op_sel_hi:[1,0]
	v_pk_mul_f32 v[68:69], v[68:69], v[36:37] op_sel_hi:[1,0]
	v_pk_mul_f32 v[66:67], v[66:67], v[36:37] op_sel_hi:[1,0]
	v_pk_mul_f32 v[64:65], v[64:65], v[36:37] op_sel_hi:[1,0]
	s_branch .LBB0_862

; __device__ __forceinline__ float fexp2(float x) { return __builtin_amdgcn_exp2f(x); }
; template <int DV, bool MASK>
; __device__ __forceinline__ void attn_softmax(f32x16 (&p)[2], f32x16 (&o)[DV / 32], float& m, float& l, float cs, int hi, int dq) {
;     if (MASK) { if (__builtin_amdgcn_readfirstlane(dq) != NO_MASK) {
; #pragma unroll
;         for (int kvb = 0; kvb < 2; ++kvb)
; #pragma unroll
;             for (int e = 0; e < 16; ++e) { const int rel = dq + 32 * kvb + (e & 3) + 8 * (e >> 2) + 4 * hi; if (rel > 128 || rel < -128) p[kvb][e] = -INFINITY; } } }
;     float mx;
;     {
;         float a0 = fmaxf(fmaxf(p[0][0], p[0][1]), p[0][2]), a1 = fmaxf(fmaxf(p[0][8], p[0][9]), p[0][10]), a2 = fmaxf(fmaxf(p[1][0], p[1][1]), p[1][2]), a3 = fmaxf(fmaxf(p[1][8], p[1][9]), p[1][10]);
;         a0 = fmaxf(fmaxf(a0, p[0][3]), p[0][4]); a1 = fmaxf(fmaxf(a1, p[0][11]), p[0][12]); a2 = fmaxf(fmaxf(a2, p[1][3]), p[1][4]); a3 = fmaxf(fmaxf(a3, p[1][11]), p[1][12]);
;         a0 = fmaxf(fmaxf(a0, p[0][5]), p[0][6]); a1 = fmaxf(fmaxf(a1, p[0][13]), p[0][14]); a2 = fmaxf(fmaxf(a2, p[1][5]), p[1][6]); a3 = fmaxf(fmaxf(a3, p[1][13]), p[1][14]);
;         a0 = fmaxf(a0, p[0][7]); a1 = fmaxf(a1, p[0][15]); a2 = fmaxf(a2, p[1][7]); a3 = fmaxf(a3, p[1][15]);
;         mx = fmaxf(fmaxf(a0, a1), fmaxf(a2, a3));
;         const auto rr = __builtin_amdgcn_permlane32_swap(__float_as_uint(mx), __float_as_uint(mx), false, false);
;         mx = fmaxf(__uint_as_float(rr[0]), __uint_as_float(rr[1])); }
;     const float mn = fmaxf(m, mx * cs);
;     if (__any(mn - m > ATT_THR)) {
;         const float alpha = fexp2(m - mn); m = mn; l *= alpha;
; #pragma unroll
;         for (int d = 0; d < DV / 32; ++d)
; #pragma unroll
;             for (int e = 0; e < 16; ++e) o[d][e] *= alpha;
;     }
.LBB0_866:
	s_nop 6
	v_max_f32_e32 v186, v113, v113
	v_max_f32_e32 v187, v112, v112
	v_max_f32_e32 v189, v105, v105
	v_max_f32_e32 v190, v104, v104
	v_max_f32_e32 v186, v187, v186
	v_max_f32_e32 v187, v121, v121
	v_max_f32_e32 v188, v120, v120
	v_max_f32_e32 v189, v190, v189
	v_max_f32_e32 v187, v188, v187
	v_max3_f32 v188, v96, v97, v98
	v_max3_f32 v189, v189, v106, v107
	v_max3_f32 v186, v186, v114, v115
	v_max3_f32 v187, v187, v122, v123
	v_max3_f32 v188, v188, v99, v100
	v_max3_f32 v189, v189, v108, v109
	v_max3_f32 v186, v186, v116, v117
	v_max3_f32 v187, v187, v124, v125
	v_max3_f32 v188, v188, v101, v102
	v_max3_f32 v189, v189, v110, v111
	v_max3_f32 v186, v186, v118, v119
	v_max3_f32 v187, v187, v126, v127
	v_max3_f32 v188, v188, v103, v189
	v_max3_f32 v186, v186, v187, v188
	v_mov_b32_e32 v187, v186
	s_nop 1
	v_permlane32_swap_b32_e32 v186, v187
	v_max_f32_e32 v186, v186, v187
	v_mul_f32_e32 v186, 0x3e38aa3b, v186
	v_max_f32_e32 v187, v167, v167
	v_max_f32_e32 v214, v187, v186
	v_sub_f32_e32 v186, v214, v167
	v_cmp_lt_f32_e32 vcc, s34, v186
	s_cbranch_vccz .LBB0_868
	v_sub_f32_e32 v167, v167, v214
	v_exp_f32_e32 v186, v167
	s_nop 0
	v_mul_f32_e32 v32, v32, v186
	v_pk_mul_f32 v[62:63], v[62:63], v[186:187] op_sel_hi:[1,0]
	v_pk_mul_f32 v[60:61], v[60:61], v[186:187] op_sel_hi:[1,0]
	v_pk_mul_f32 v[58:59], v[58:59], v[186:187] op_sel_hi:[1,0]
	v_pk_mul_f32 v[56:57], v[56:57], v[186:187] op_sel_hi:[1,0]
	v_pk_mul_f32 v[54:55], v[54:55], v[186:187] op_sel_hi:[1,0]
	v_pk_mul_f32 v[52:53], v[52:53], v[186:187] op_sel_hi:[1,0]
	v_pk_mul_f32 v[50:51], v[50:51], v[186:187] op_sel_hi:[1,0]
	v_pk_mul_f32 v[48:49], v[48:49], v[186:187] op_sel_hi:[1,0]
	v_pk_mul_f32 v[16:17], v[16:17], v[186:187] op_sel_hi:[1,0]
	v_pk_mul_f32 v[14:15], v[14:15], v[186:187] op_sel_hi:[1,0]
	v_pk_mul_f32 v[12:13], v[12:13], v[186:187] op_sel_hi:[1,0]
	v_pk_mul_f32 v[10:11], v[10:11], v[186:187] op_sel_hi:[1,0]
	v_pk_mul_f32 v[8:9], v[8:9], v[186:187] op_sel_hi:[1,0]
	v_pk_mul_f32 v[6:7], v[6:7], v[186:187] op_sel_hi:[1,0]
	v_pk_mul_f32 v[4:5], v[4:5], v[186:187] op_sel_hi:[1,0]
	v_pk_mul_f32 v[2:3], v[2:3], v[186:187] op_sel_hi:[1,0]
	s_branch .LBB0_869

; __device__ __forceinline__ float fexp(float x) { return __builtin_amdgcn_exp2f(x * LOG2E); }
; __device__ __forceinline__ float logsigf_(float x) { return fminf(x, 0.f) - log1pf(expf(-fabsf(x))); }
; __device__ __forceinline__ float scan_max(float v, int dir, int lane) {
; #pragma unroll
;     for (int o = 1; o < 64; o <<= 1) { const float t = dir == 0 ? __shfl_up(v, o) : __shfl_down(v, o); const bool ok = dir == 0 ? (lane >= o) : (lane + o < 64); if (ok) v = fmaxf(v, t); }
;     return v;
; }
; __device__ __forceinline__ void mlstm_c_phase(int u_first, int G, bool skip_ctx, const bf16* Z, const float* GATES, const float* gbias, const float* gh  , const bf16* DC, const float* DN, const float* SC,
;                                               bf16* Y, LAS unsigned char* L, int tid) {
;     ...
;     if (w4 == 0) {
;         const float bs = scan_sum(logsigf_(pfp), dir, lane);
;         const float u = pig - bs, pm = scan_max(u, dir, lane), m_in = pmin;
;         const float mt = bs + fmaxf(m_in, pm);
;         bq[lane] = bs - mt; uu[lane] = u; iwv[lane] = fexp(bs + m_in - mt); emt[lane] = fexp(-mt); nin[lane] = pnin;
;     }
.LBB0_914:
	s_or_b64 exec, exec, s[26:27]
	v_cmp_eq_u32_e64 s[16:17], v63, v41
	s_waitcnt lgkmcnt(0)
	v_max_f32_e32 v41, v56, v56
	v_max_f32_e32 v41, v47, v41
	v_cndmask_b32_e64 v41, v41, v47, s[16:17]
	s_and_saveexec_b64 s[16:17], vcc
	s_xor_b64 s[26:27], exec, s[16:17]
	v_cmp_eq_u32_e64 s[16:17], 62, v40
	s_nop 1
	v_cndmask_b32_e64 v40, 2, 0, s[16:17]
	v_add_lshl_u32 v40, v40, v185, 2
	ds_bpermute_b32 v42, v40, v41
	s_andn2_saveexec_b64 s[26:27], s[26:27]
	s_cbranch_execz .LBB0_918
	v_cmp_lt_i32_e64 s[16:17], v44, v39
	s_nop 1
	v_cndmask_b32_e64 v40, v44, v185, s[16:17]
	v_lshlrev_b32_e32 v40, 2, v40
	s_waitcnt lgkmcnt(0)
	ds_bpermute_b32 v42, v40, v41
.LBB0_918:
	s_or_b64 exec, exec, s[26:27]
	s_waitcnt lgkmcnt(0)
	v_max_f32_e32 v40, v42, v42
	v_max_f32_e32 v40, v41, v40
	v_cndmask_b32_e64 v40, v41, v40, s[4:5]
	s_and_saveexec_b64 s[4:5], vcc
	s_xor_b64 s[16:17], exec, s[4:5]
	v_cmp_eq_u32_e64 s[4:5], 60, v43
	s_nop 1
	v_cndmask_b32_e64 v41, 4, 0, s[4:5]
	v_add_lshl_u32 v41, v41, v185, 2
	ds_bpermute_b32 v41, v41, v40
	s_andn2_saveexec_b64 s[16:17], s[16:17]
	s_cbranch_execz .LBB0_922
	v_cmp_lt_i32_e64 s[4:5], v46, v39
	s_waitcnt lgkmcnt(0)
	s_nop 0
	v_cndmask_b32_e64 v41, v46, v185, s[4:5]
	v_lshlrev_b32_e32 v41, 2, v41
	ds_bpermute_b32 v41, v41, v40
.LBB0_922:
	s_or_b64 exec, exec, s[16:17]
	s_waitcnt lgkmcnt(0)
	v_max_f32_e32 v41, v41, v41
	v_max_f32_e32 v41, v40, v41
	v_cndmask_b32_e64 v40, v40, v41, s[8:9]
	s_and_saveexec_b64 s[4:5], vcc
	s_xor_b64 s[8:9], exec, s[4:5]
	v_cmp_eq_u32_e64 s[4:5], 56, v45
	s_nop 1
	v_cndmask_b32_e64 v41, 8, 0, s[4:5]
	v_add_lshl_u32 v41, v41, v185, 2
	ds_bpermute_b32 v41, v41, v40
	s_andn2_saveexec_b64 s[8:9], s[8:9]
	s_cbranch_execz .LBB0_926
	v_cmp_lt_i32_e64 s[4:5], v50, v39
	s_waitcnt lgkmcnt(0)
	s_nop 0
	v_cndmask_b32_e64 v41, v50, v185, s[4:5]
	v_lshlrev_b32_e32 v41, 2, v41
	ds_bpermute_b32 v41, v41, v40
.LBB0_926:
	s_or_b64 exec, exec, s[8:9]
	s_waitcnt lgkmcnt(0)
	v_max_f32_e32 v41, v41, v41
	v_max_f32_e32 v41, v40, v41
	v_cndmask_b32_e64 v40, v40, v41, s[10:11]
	s_and_saveexec_b64 s[4:5], vcc
	s_xor_b64 s[8:9], exec, s[4:5]
	v_cmp_eq_u32_e64 s[4:5], 48, v49
	s_nop 1
	v_cndmask_b32_e64 v41, 16, 0, s[4:5]
	v_add_lshl_u32 v41, v41, v185, 2
	ds_bpermute_b32 v41, v41, v40
	s_andn2_saveexec_b64 s[8:9], s[8:9]
	s_cbranch_execz .LBB0_930
	v_cmp_lt_i32_e64 s[4:5], v52, v39
	s_waitcnt lgkmcnt(0)
	s_nop 0
	v_cndmask_b32_e64 v41, v52, v185, s[4:5]
	v_lshlrev_b32_e32 v41, 2, v41
	ds_bpermute_b32 v41, v41, v40
.LBB0_930:
	s_or_b64 exec, exec, s[8:9]
	s_waitcnt lgkmcnt(0)
	v_max_f32_e32 v41, v41, v41
	v_max_f32_e32 v41, v40, v41
	v_cndmask_b32_e64 v40, v40, v41, s[14:15]
	s_and_saveexec_b64 s[4:5], vcc
	s_xor_b64 s[4:5], exec, s[4:5]
	ds_bpermute_b32 v41, v51, v40
	s_andn2_saveexec_b64 s[4:5], s[4:5]
	s_cbranch_execz .LBB0_934
	v_cmp_lt_i32_e32 vcc, v53, v39
	s_nop 1
	v_cndmask_b32_e32 v39, v53, v185, vcc
	v_lshlrev_b32_e32 v39, 2, v39
	s_waitcnt lgkmcnt(0)
	ds_bpermute_b32 v41, v39, v40
.LBB0_934:
	s_or_b64 exec, exec, s[4:5]
	s_waitcnt lgkmcnt(0)
	v_max_f32_e32 v39, v41, v41
	v_max_f32_e32 v39, v40, v39
	v_cndmask_b32_e64 v39, v40, v39, s[12:13]
	v_max_f32_e32 v39, v39, v39
	v_max_f32_e32 v39, v140, v39
	v_add_f32_e32 v39, v48, v39
	v_add_f32_e32 v40, v140, v48
	v_sub_f32_e32 v40, v40, v39
	v_mul_f32_e32 v40, 0x3fb8aa3b, v40
	v_mul_f32_e32 v41, 0xbfb8aa3b, v39
	v_exp_f32_e32 v40, v40
	v_exp_f32_e32 v41, v41
	v_sub_f32_e32 v39, v48, v39
	v_lshl_add_u32 v42, v63, 2, v147
	ds_write2st64_b32 v42, v39, v47 offset1:1
	ds_write2st64_b32 v42, v40, v41 offset0:2 offset1:3
	ds_write_b32 v42, v141 offset:1280

; template <int DQK, int KSB>
; __device__ __forceinline__ void attn_scores(LAS const unsigned char* Kt, const bf16x8 (&qf)[DQK / 16], f32x16 (&p)[2], int r32, int hi) {
;     constexpr int NK = DQK / 16;
;     LAS const unsigned char* kp = Kt + r32 * KSB + hi * 16;
;     f32x16 p0, p1;
; #pragma unroll
;     for (int e = 0; e < 16; ++e) { p0[e] = 0.f; p1[e] = 0.f; }
;     bf16x8 kr[3][2];
;     ...
;     QK_LOAD(0); QK_LOAD(1); SCHED_FENCE();
; #pragma unroll
;     for (int ks = 0; ks < NK; ++ks) {
;         if (ks + 2 < NK) QK_LOAD(ks + 2);
;         p0 = MFMA32(kr[ks % 3][0], qf[ks], p0); p1 = MFMA32(kr[ks % 3][1], qf[ks], p1); SCHED_FENCE();
;     }
;     ...
;     p[0] = p0; p[1] = p1;
; }
; template <int DV, bool MASK>
; __device__ __forceinline__ void attn_softmax(f32x16 (&p)[2], f32x16 (&o)[DV / 32], float& m, float& l, float cs, int hi, int dq) {
;     if (MASK) { if (__builtin_amdgcn_readfirstlane(dq) != NO_MASK) {
; #pragma unroll
;         for (int kvb = 0; kvb < 2; ++kvb)
; #pragma unroll
;             for (int e = 0; e < 16; ++e) { const int rel = dq + 32 * kvb + (e & 3) + 8 * (e >> 2) + 4 * hi; if (rel > 128 || rel < -128) p[kvb][e] = -INFINITY; } } }
;     float mx;
;     {
;         float a0 = fmaxf(fmaxf(p[0][0], p[0][1]), p[0][2]), a1 = fmaxf(fmaxf(p[0][8], p[0][9]), p[0][10]), a2 = fmaxf(fmaxf(p[1][0], p[1][1]), p[1][2]), a3 = fmaxf(fmaxf(p[1][8], p[1][9]), p[1][10]);
;         a0 = fmaxf(fmaxf(a0, p[0][3]), p[0][4]); a1 = fmaxf(fmaxf(a1, p[0][11]), p[0][12]); a2 = fmaxf(fmaxf(a2, p[1][3]), p[1][4]); a3 = fmaxf(fmaxf(a3, p[1][11]), p[1][12]);
;         a0 = fmaxf(fmaxf(a0, p[0][5]), p[0][6]); a1 = fmaxf(fmaxf(a1, p[0][13]), p[0][14]); a2 = fmaxf(fmaxf(a2, p[1][5]), p[1][6]); a3 = fmaxf(fmaxf(a3, p[1][13]), p[1][14]);
;         a0 = fmaxf(a0, p[0][7]); a1 = fmaxf(a1, p[0][15]); a2 = fmaxf(a2, p[1][7]); a3 = fmaxf(a3, p[1][15]);
; __device__ __forceinline__ void mla_unit(const bf16* QM, const bf16* KVM, const bf16* KR, bf16* Y, int b, int h, int qrow0, int ntiles, bool latent, LAS unsigned char* L, int tid_in) {
;     ...
;     for (int t = 0; t < ntiles; ++t) {
;         LAS const unsigned char* Kt = L + bcur * MLA_BUF;
;         f32x16 p[2];
;         __builtin_amdgcn_sched_barrier(0);
;         attn_scores<192, MLA_KSB>(Kt, qf, p, r32, hi);
;         __syncthreads();
;         attn_softmax<128, false>(p, o, m, l, cs, hi, 0);
.LBB0_955:
	s_mul_i32 s10, s9, 0xb400
	s_add_i32 s10, s10, 0
	v_add3_u32 v186, s10, v198, v32
	ds_read_b128 v[82:85], v186
	ds_read_b128 v[202:205], v186 offset:32
	ds_read_b128 v[86:89], v186 offset:12800
	ds_read_b128 v[206:209], v186 offset:12832
	s_waitcnt lgkmcnt(3)
	v_mfma_f32_32x32x16_bf16 v[98:113], v[82:85], v[18:21], 0
	ds_read_b128 v[210:213], v186 offset:64
	ds_read_b128 v[214:217], v186 offset:12864
	s_waitcnt lgkmcnt(3)
	v_mfma_f32_32x32x16_bf16 v[82:97], v[86:89], v[18:21], 0
	v_mfma_f32_32x32x16_bf16 v[98:113], v[202:205], v[22:25], v[98:113]
	ds_read_b128 v[202:205], v186 offset:96
	ds_read_b128 v[218:221], v186 offset:12896
	s_waitcnt lgkmcnt(4)
	v_mfma_f32_32x32x16_bf16 v[82:97], v[206:209], v[22:25], v[82:97]
	s_waitcnt lgkmcnt(3)
	v_mfma_f32_32x32x16_bf16 v[98:113], v[210:213], v[26:29], v[98:113]
	ds_read_b128 v[206:209], v186 offset:128
	ds_read_b128 v[210:213], v186 offset:12928
	s_waitcnt lgkmcnt(4)
	v_mfma_f32_32x32x16_bf16 v[82:97], v[214:217], v[26:29], v[82:97]
	s_waitcnt lgkmcnt(3)
	v_mfma_f32_32x32x16_bf16 v[98:113], v[202:205], v[114:117], v[98:113]
	ds_read_b128 v[202:205], v186 offset:160
	ds_read_b128 v[214:217], v186 offset:12960
	s_waitcnt lgkmcnt(4)
	v_mfma_f32_32x32x16_bf16 v[82:97], v[218:221], v[114:117], v[82:97]
	s_waitcnt lgkmcnt(3)
	v_mfma_f32_32x32x16_bf16 v[98:113], v[206:209], v[118:121], v[98:113]
	ds_read_b128 v[206:209], v186 offset:192
	ds_read_b128 v[218:221], v186 offset:12992
	s_waitcnt lgkmcnt(4)
	v_mfma_f32_32x32x16_bf16 v[82:97], v[210:213], v[118:121], v[82:97]
	s_waitcnt lgkmcnt(3)
	v_mfma_f32_32x32x16_bf16 v[98:113], v[202:205], v[122:125], v[98:113]
	ds_read_b128 v[202:205], v186 offset:224
	ds_read_b128 v[210:213], v186 offset:13024
	s_waitcnt lgkmcnt(4)
	v_mfma_f32_32x32x16_bf16 v[82:97], v[214:217], v[122:125], v[82:97]
	s_waitcnt lgkmcnt(3)
	v_mfma_f32_32x32x16_bf16 v[98:113], v[206:209], v[126:129], v[98:113]
	ds_read_b128 v[206:209], v186 offset:256
	ds_read_b128 v[214:217], v186 offset:13056
	s_waitcnt lgkmcnt(4)
	v_mfma_f32_32x32x16_bf16 v[82:97], v[218:221], v[126:129], v[82:97]
	s_waitcnt lgkmcnt(3)
	v_mfma_f32_32x32x16_bf16 v[98:113], v[202:205], v[130:133], v[98:113]
	ds_read_b128 v[202:205], v186 offset:288
	ds_read_b128 v[218:221], v186 offset:13088
	s_waitcnt lgkmcnt(4)
	v_mfma_f32_32x32x16_bf16 v[82:97], v[210:213], v[130:133], v[82:97]
	s_waitcnt lgkmcnt(3)
	v_mfma_f32_32x32x16_bf16 v[98:113], v[206:209], v[134:137], v[98:113]
	ds_read_b128 v[206:209], v186 offset:320
	ds_read_b128 v[210:213], v186 offset:13120
	s_waitcnt lgkmcnt(4)
	v_mfma_f32_32x32x16_bf16 v[82:97], v[214:217], v[134:137], v[82:97]
	s_waitcnt lgkmcnt(3)
	v_mfma_f32_32x32x16_bf16 v[98:113], v[202:205], v[138:141], v[98:113]
	ds_read_b128 v[202:205], v186 offset:352
	ds_read_b128 v[214:217], v186 offset:13152
	s_waitcnt lgkmcnt(4)
	v_mfma_f32_32x32x16_bf16 v[82:97], v[218:221], v[138:141], v[82:97]
	s_waitcnt lgkmcnt(3)
	v_mfma_f32_32x32x16_bf16 v[98:113], v[206:209], v[142:145], v[98:113]
	s_waitcnt lgkmcnt(2)
	v_mfma_f32_32x32x16_bf16 v[82:97], v[210:213], v[142:145], v[82:97]
	s_waitcnt lgkmcnt(1)
	v_mfma_f32_32x32x16_bf16 v[98:113], v[202:205], v[146:149], v[98:113]
	s_waitcnt lgkmcnt(0)
	v_mfma_f32_32x32x16_bf16 v[82:97], v[214:217], v[146:149], v[82:97]
	s_nop 9
	v_max_f32_e32 v186, v99, v99
	v_max_f32_e32 v187, v98, v98
	v_max_f32_e32 v189, v91, v91
	v_max_f32_e32 v190, v90, v90
	v_max_f32_e32 v186, v187, v186
	v_max_f32_e32 v187, v107, v107
	v_max_f32_e32 v188, v106, v106
	v_max_f32_e32 v189, v190, v189
	v_max_f32_e32 v187, v188, v187
	v_max3_f32 v188, v82, v83, v84
	v_max3_f32 v189, v189, v92, v93
	v_max3_f32 v186, v186, v100, v101
	v_max3_f32 v187, v187, v108, v109
	v_max3_f32 v188, v188, v85, v86
	v_max3_f32 v189, v189, v94, v95
	v_max3_f32 v186, v186, v102, v103
	v_max3_f32 v187, v187, v110, v111
	v_max3_f32 v188, v188, v87, v88
	v_max3_f32 v189, v189, v96, v97
	v_max3_f32 v186, v186, v104, v105
	v_max3_f32 v187, v187, v112, v113
	v_max3_f32 v188, v188, v89, v189
	v_max3_f32 v186, v186, v187, v188
	v_mov_b32_e32 v187, v186
	s_nop 1
	v_permlane32_swap_b32_e32 v186, v187
	v_max_f32_e32 v186, v186, v187
	v_mul_f32_e32 v186, 0x3dd53b94, v186
	v_max_f32_e32 v187, v200, v200
	v_max_f32_e32 v199, v187, v186
	v_sub_f32_e32 v186, v199, v200
	v_cmp_lt_f32_e32 vcc, s34, v186
	s_barrier
	s_cbranch_vccz .LBB0_957
	v_sub_f32_e32 v186, v200, v199
	v_exp_f32_e32 v186, v186
	s_nop 0
	v_mul_f32_e32 v173, v173, v186
	v_pk_mul_f32 v[80:81], v[80:81], v[186:187] op_sel_hi:[1,0]
	v_pk_mul_f32 v[78:79], v[78:79], v[186:187] op_sel_hi:[1,0]
	v_pk_mul_f32 v[76:77], v[76:77], v[186:187] op_sel_hi:[1,0]
	v_pk_mul_f32 v[74:75], v[74:75], v[186:187] op_sel_hi:[1,0]
	v_pk_mul_f32 v[72:73], v[72:73], v[186:187] op_sel_hi:[1,0]
	v_pk_mul_f32 v[70:71], v[70:71], v[186:187] op_sel_hi:[1,0]
	v_pk_mul_f32 v[68:69], v[68:69], v[186:187] op_sel_hi:[1,0]
	v_pk_mul_f32 v[66:67], v[66:67], v[186:187] op_sel_hi:[1,0]
	v_pk_mul_f32 v[64:65], v[64:65], v[186:187] op_sel_hi:[1,0]
	v_pk_mul_f32 v[62:63], v[62:63], v[186:187] op_sel_hi:[1,0]
	v_pk_mul_f32 v[60:61], v[60:61], v[186:187] op_sel_hi:[1,0]
	v_pk_mul_f32 v[58:59], v[58:59], v[186:187] op_sel_hi:[1,0]
	v_pk_mul_f32 v[56:57], v[56:57], v[186:187] op_sel_hi:[1,0]
	v_pk_mul_f32 v[54:55], v[54:55], v[186:187] op_sel_hi:[1,0]
	v_pk_mul_f32 v[52:53], v[52:53], v[186:187] op_sel_hi:[1,0]
	v_pk_mul_f32 v[50:51], v[50:51], v[186:187] op_sel_hi:[1,0]
	v_pk_mul_f32 v[48:49], v[48:49], v[186:187] op_sel_hi:[1,0]
	v_pk_mul_f32 v[46:47], v[46:47], v[186:187] op_sel_hi:[1,0]
	v_pk_mul_f32 v[44:45], v[44:45], v[186:187] op_sel_hi:[1,0]
	v_pk_mul_f32 v[42:43], v[42:43], v[186:187] op_sel_hi:[1,0]
	v_pk_mul_f32 v[40:41], v[40:41], v[186:187] op_sel_hi:[1,0]
	v_pk_mul_f32 v[38:39], v[38:39], v[186:187] op_sel_hi:[1,0]
	v_pk_mul_f32 v[36:37], v[36:37], v[186:187] op_sel_hi:[1,0]
	v_pk_mul_f32 v[34:35], v[34:35], v[186:187] op_sel_hi:[1,0]
	v_pk_mul_f32 v[16:17], v[16:17], v[186:187] op_sel_hi:[1,0]
	v_pk_mul_f32 v[14:15], v[14:15], v[186:187] op_sel_hi:[1,0]
	v_pk_mul_f32 v[12:13], v[12:13], v[186:187] op_sel_hi:[1,0]
	v_pk_mul_f32 v[10:11], v[10:11], v[186:187] op_sel_hi:[1,0]
	v_pk_mul_f32 v[8:9], v[8:9], v[186:187] op_sel_hi:[1,0]
	v_pk_mul_f32 v[6:7], v[6:7], v[186:187] op_sel_hi:[1,0]
	v_pk_mul_f32 v[4:5], v[4:5], v[186:187] op_sel_hi:[1,0]
	v_pk_mul_f32 v[2:3], v[2:3], v[186:187] op_sel_hi:[1,0]
	s_branch .LBB0_958

; template <int DQK, int KSB>
; __device__ __forceinline__ void attn_scores(LAS const unsigned char* Kt, const bf16x8 (&qf)[DQK / 16], f32x16 (&p)[2], int r32, int hi) {
;     constexpr int NK = DQK / 16;
;     LAS const unsigned char* kp = Kt + r32 * KSB + hi * 16;
;     f32x16 p0, p1;
; #pragma unroll
;     for (int e = 0; e < 16; ++e) { p0[e] = 0.f; p1[e] = 0.f; }
;     bf16x8 kr[3][2];
;     ...
;     QK_LOAD(0); QK_LOAD(1); SCHED_FENCE();
; #pragma unroll
;     for (int ks = 0; ks < NK; ++ks) {
;         if (ks + 2 < NK) QK_LOAD(ks + 2);
;         p0 = MFMA32(kr[ks % 3][0], qf[ks], p0); p1 = MFMA32(kr[ks % 3][1], qf[ks], p1); SCHED_FENCE();
;     }
;     ...
;     p[0] = p0; p[1] = p1;
; }
; template <int DV, bool MASK>
; __device__ __forceinline__ void attn_softmax(f32x16 (&p)[2], f32x16 (&o)[DV / 32], float& m, float& l, float cs, int hi, int dq) {
;     if (MASK) { if (__builtin_amdgcn_readfirstlane(dq) != NO_MASK) {
; #pragma unroll
;         for (int kvb = 0; kvb < 2; ++kvb)
; #pragma unroll
;             for (int e = 0; e < 16; ++e) { const int rel = dq + 32 * kvb + (e & 3) + 8 * (e >> 2) + 4 * hi; if (rel > 128 || rel < -128) p[kvb][e] = -INFINITY; } } }
;     float mx;
;     {
;         float a0 = fmaxf(fmaxf(p[0][0], p[0][1]), p[0][2]), a1 = fmaxf(fmaxf(p[0][8], p[0][9]), p[0][10]), a2 = fmaxf(fmaxf(p[1][0], p[1][1]), p[1][2]), a3 = fmaxf(fmaxf(p[1][8], p[1][9]), p[1][10]);
;         a0 = fmaxf(fmaxf(a0, p[0][3]), p[0][4]); a1 = fmaxf(fmaxf(a1, p[0][11]), p[0][12]); a2 = fmaxf(fmaxf(a2, p[1][3]), p[1][4]); a3 = fmaxf(fmaxf(a3, p[1][11]), p[1][12]);
;         a0 = fmaxf(fmaxf(a0, p[0][5]), p[0][6]); a1 = fmaxf(fmaxf(a1, p[0][13]), p[0][14]); a2 = fmaxf(fmaxf(a2, p[1][5]), p[1][6]); a3 = fmaxf(fmaxf(a3, p[1][13]), p[1][14]);
;         a0 = fmaxf(a0, p[0][7]); a1 = fmaxf(a1, p[0][15]); a2 = fmaxf(a2, p[1][7]); a3 = fmaxf(a3, p[1][15]);
; __device__ __forceinline__ void mla_unit(const bf16* QM, const bf16* KVM, const bf16* KR, bf16* Y, int b, int h, int qrow0, int ntiles, bool latent, LAS unsigned char* L, int tid_in) {
;     ...
;     for (int t = 0; t < ntiles; ++t) {
;         LAS const unsigned char* Kt = L + bcur * MLA_BUF;
;         f32x16 p[2];
;         __builtin_amdgcn_sched_barrier(0);
;         attn_scores<192, MLA_KSB>(Kt, qf, p, r32, hi);
;         __syncthreads();
;         attn_softmax<128, false>(p, o, m, l, cs, hi, 0);
.LBB0_970:
	s_mul_i32 s12, s11, 0xb400
	s_add_i32 s12, s12, 0
	v_add3_u32 v32, s12, v207, v30
	ds_read_b128 v[34:37], v32
	ds_read_b128 v[38:41], v32 offset:32
	ds_read_b128 v[42:45], v32 offset:12800
	ds_read_b128 v[210:213], v32 offset:12832
	s_waitcnt lgkmcnt(3)
	v_mfma_f32_32x32x16_bf16 v[112:127], v[34:37], v[18:21], 0
	ds_read_b128 v[34:37], v32 offset:64
	ds_read_b128 v[214:217], v32 offset:12864
	s_waitcnt lgkmcnt(3)
	v_mfma_f32_32x32x16_bf16 v[96:111], v[42:45], v[18:21], 0
	v_mfma_f32_32x32x16_bf16 v[112:127], v[38:41], v[22:25], v[112:127]
	ds_read_b128 v[38:41], v32 offset:96
	ds_read_b128 v[42:45], v32 offset:12896
	s_waitcnt lgkmcnt(4)
	v_mfma_f32_32x32x16_bf16 v[96:111], v[210:213], v[22:25], v[96:111]
	s_waitcnt lgkmcnt(3)
	v_mfma_f32_32x32x16_bf16 v[112:127], v[34:37], v[26:29], v[112:127]
	ds_read_b128 v[34:37], v32 offset:128
	ds_read_b128 v[210:213], v32 offset:12928
	s_waitcnt lgkmcnt(4)
	v_mfma_f32_32x32x16_bf16 v[96:111], v[214:217], v[26:29], v[96:111]
	s_waitcnt lgkmcnt(3)
	v_mfma_f32_32x32x16_bf16 v[112:127], v[38:41], v[128:131], v[112:127]
	ds_read_b128 v[38:41], v32 offset:160
	ds_read_b128 v[214:217], v32 offset:12960
	s_waitcnt lgkmcnt(4)
	v_mfma_f32_32x32x16_bf16 v[96:111], v[42:45], v[128:131], v[96:111]
	s_waitcnt lgkmcnt(3)
	v_mfma_f32_32x32x16_bf16 v[112:127], v[34:37], v[132:135], v[112:127]
	ds_read_b128 v[34:37], v32 offset:192
	ds_read_b128 v[42:45], v32 offset:12992
	s_waitcnt lgkmcnt(4)
	v_mfma_f32_32x32x16_bf16 v[96:111], v[210:213], v[132:135], v[96:111]
	s_waitcnt lgkmcnt(3)
	v_mfma_f32_32x32x16_bf16 v[112:127], v[38:41], v[136:139], v[112:127]
	ds_read_b128 v[38:41], v32 offset:224
	ds_read_b128 v[210:213], v32 offset:13024
	s_waitcnt lgkmcnt(4)
	v_mfma_f32_32x32x16_bf16 v[96:111], v[214:217], v[136:139], v[96:111]
	s_waitcnt lgkmcnt(3)
	v_mfma_f32_32x32x16_bf16 v[112:127], v[34:37], v[140:143], v[112:127]
	ds_read_b128 v[34:37], v32 offset:256
	ds_read_b128 v[214:217], v32 offset:13056
	s_waitcnt lgkmcnt(4)
	v_mfma_f32_32x32x16_bf16 v[96:111], v[42:45], v[140:143], v[96:111]
	s_waitcnt lgkmcnt(3)
	v_mfma_f32_32x32x16_bf16 v[112:127], v[38:41], v[144:147], v[112:127]
	ds_read_b128 v[38:41], v32 offset:288
	ds_read_b128 v[42:45], v32 offset:13088
	s_waitcnt lgkmcnt(4)
	v_mfma_f32_32x32x16_bf16 v[96:111], v[210:213], v[144:147], v[96:111]
	s_waitcnt lgkmcnt(3)
	v_mfma_f32_32x32x16_bf16 v[112:127], v[34:37], v[152:155], v[112:127]
	ds_read_b128 v[34:37], v32 offset:320
	ds_read_b128 v[210:213], v32 offset:13120
	s_waitcnt lgkmcnt(4)
	v_mfma_f32_32x32x16_bf16 v[96:111], v[214:217], v[152:155], v[96:111]
	s_waitcnt lgkmcnt(3)
	v_mfma_f32_32x32x16_bf16 v[112:127], v[38:41], v[148:151], v[112:127]
	ds_read_b128 v[38:41], v32 offset:352
	ds_read_b128 v[214:217], v32 offset:13152
	s_waitcnt lgkmcnt(4)
	v_mfma_f32_32x32x16_bf16 v[96:111], v[42:45], v[148:151], v[96:111]
	s_waitcnt lgkmcnt(3)
	v_mfma_f32_32x32x16_bf16 v[112:127], v[34:37], v[160:163], v[112:127]
	s_waitcnt lgkmcnt(2)
	v_mfma_f32_32x32x16_bf16 v[96:111], v[210:213], v[160:163], v[96:111]
	s_waitcnt lgkmcnt(1)
	v_mfma_f32_32x32x16_bf16 v[112:127], v[38:41], v[156:159], v[112:127]
	s_waitcnt lgkmcnt(0)
	v_mfma_f32_32x32x16_bf16 v[96:111], v[214:217], v[156:159], v[96:111]
	s_nop 10
	v_max_f32_e32 v32, v112, v113
	v_max_f32_e32 v36, v104, v105
	v_max_f32_e32 v34, v120, v121
	v_max3_f32 v35, v96, v97, v98
	v_max3_f32 v36, v36, v106, v107
	v_max3_f32 v32, v32, v114, v115
	v_max3_f32 v34, v34, v122, v123
	v_max3_f32 v35, v35, v99, v100
	v_max3_f32 v36, v36, v108, v109
	v_max3_f32 v32, v32, v116, v117
	v_max3_f32 v34, v34, v124, v125
	v_max3_f32 v35, v35, v101, v102
	v_max3_f32 v36, v36, v110, v111
	v_max3_f32 v32, v32, v118, v119
	v_max3_f32 v34, v34, v126, v127
	v_max3_f32 v35, v35, v103, v36
	v_max3_f32 v32, v32, v34, v35
	v_mov_b32_e32 v34, v32
	s_nop 1
	v_permlane32_swap_b32_e32 v32, v34
	v_max_f32_e32 v32, v32, v34
	v_mul_f32_e32 v32, 0x3dd53b94, v32
	v_max_f32_e32 v32, v208, v32
	v_sub_f32_e32 v34, v32, v208
	v_cmp_lt_f32_e32 vcc, s34, v34
	s_barrier
	s_cbranch_vccz .LBB0_972
	v_sub_f32_e32 v34, v208, v32
	v_exp_f32_e32 v34, v34
	s_nop 0
	v_mul_f32_e32 v201, v201, v34
	v_pk_mul_f32 v[94:95], v[94:95], v[34:35] op_sel_hi:[1,0]
	v_pk_mul_f32 v[92:93], v[92:93], v[34:35] op_sel_hi:[1,0]
	v_pk_mul_f32 v[90:91], v[90:91], v[34:35] op_sel_hi:[1,0]
	v_pk_mul_f32 v[88:89], v[88:89], v[34:35] op_sel_hi:[1,0]
	v_pk_mul_f32 v[86:87], v[86:87], v[34:35] op_sel_hi:[1,0]
	v_pk_mul_f32 v[84:85], v[84:85], v[34:35] op_sel_hi:[1,0]
	v_pk_mul_f32 v[82:83], v[82:83], v[34:35] op_sel_hi:[1,0]
	v_pk_mul_f32 v[80:81], v[80:81], v[34:35] op_sel_hi:[1,0]
	v_pk_mul_f32 v[78:79], v[78:79], v[34:35] op_sel_hi:[1,0]
	v_pk_mul_f32 v[76:77], v[76:77], v[34:35] op_sel_hi:[1,0]
	v_pk_mul_f32 v[74:75], v[74:75], v[34:35] op_sel_hi:[1,0]
	v_pk_mul_f32 v[72:73], v[72:73], v[34:35] op_sel_hi:[1,0]
	v_pk_mul_f32 v[70:71], v[70:71], v[34:35] op_sel_hi:[1,0]
	v_pk_mul_f32 v[68:69], v[68:69], v[34:35] op_sel_hi:[1,0]
	v_pk_mul_f32 v[66:67], v[66:67], v[34:35] op_sel_hi:[1,0]
	v_pk_mul_f32 v[64:65], v[64:65], v[34:35] op_sel_hi:[1,0]
	v_pk_mul_f32 v[62:63], v[62:63], v[34:35] op_sel_hi:[1,0]
	v_pk_mul_f32 v[60:61], v[60:61], v[34:35] op_sel_hi:[1,0]
	v_pk_mul_f32 v[58:59], v[58:59], v[34:35] op_sel_hi:[1,0]
	v_pk_mul_f32 v[56:57], v[56:57], v[34:35] op_sel_hi:[1,0]
	v_pk_mul_f32 v[54:55], v[54:55], v[34:35] op_sel_hi:[1,0]
	v_pk_mul_f32 v[52:53], v[52:53], v[34:35] op_sel_hi:[1,0]
	v_pk_mul_f32 v[50:51], v[50:51], v[34:35] op_sel_hi:[1,0]
	v_pk_mul_f32 v[48:49], v[48:49], v[34:35] op_sel_hi:[1,0]
	v_pk_mul_f32 v[16:17], v[16:17], v[34:35] op_sel_hi:[1,0]
	v_pk_mul_f32 v[14:15], v[14:15], v[34:35] op_sel_hi:[1,0]
	v_pk_mul_f32 v[12:13], v[12:13], v[34:35] op_sel_hi:[1,0]
	v_pk_mul_f32 v[10:11], v[10:11], v[34:35] op_sel_hi:[1,0]
	v_pk_mul_f32 v[8:9], v[8:9], v[34:35] op_sel_hi:[1,0]
	v_pk_mul_f32 v[6:7], v[6:7], v[34:35] op_sel_hi:[1,0]
	v_pk_mul_f32 v[4:5], v[4:5], v[34:35] op_sel_hi:[1,0]
	v_pk_mul_f32 v[2:3], v[2:3], v[34:35] op_sel_hi:[1,0]
	s_branch .LBB0_973
